# attention tiles: half-wave running-max exchange by v_permlane32_swap instead of ds_bpermute (on top of the flag barrier)
# speedup vs baseline: 1.0104x; 1.0033x over previous
; #define MFMA32(a, b, c) __builtin_amdgcn_mfma_f32_32x32x16_bf16((a), (b), (c), 0, 0, 0)
; template <int KSTRIDE, bool WIN, int MASK, int MODE>
; DI void attend_tile(const u16* Ks, const u16* Vts, const bf16x8 (&qf)[4], f32x16 (&O)[2], float& m, float& l, int dbase,
;                     float slope2, bool lanesel, float invl, unsigned* imp_row, int mbase, int lr, int hh) {
;   f32x16 s[2];
; #pragma unroll
;   for (int kt = 0; kt < 2; ++kt) {
; #pragma unroll
;     for (int e = 0; e < 16; ++e) s[kt][e] = 0.f;
; #pragma unroll
;     for (int ks = 0; ks < 4; ++ks) {
;       bf16x8 a = *(const bf16x8*)(Ks + (kt * 32 + lr) * 72 + ks * 16 + hh * 8);
;       s[kt] = MFMA32(a, qf[ks], s[kt]);
;     }
;   }
;   const float fd0 = (float)(dbase - KSTRIDE * 4 * hh);
;   const float ct = slope2 * fd0;
;   float mx = -1e30f;
; #pragma unroll
;   for (int kt = 0; kt < 2; ++kt)
; #pragma unroll
;     for (int e = 0; e < 16; ++e) {
;       const float Ke = (float)(KSTRIDE * (kt * 32 + (e & 3) + 8 * (e >> 2)));
;       float v = fmaf(slope2, Ke, s[kt][e]);
;       if (MASK == 1) {
;         const float fd = fd0 - Ke;
;         bool valid = fd >= 0.f;
;         if (WIN) valid = valid && (fd < 512.f);
;         valid = valid && lanesel;
;         v = valid ? v : -1e30f;
;       }
;       s[kt][e] = v;
;       mx = fmaxf(mx, v);
;     }
;   mx = (mx > -1e29f) ? mx - ct : -1e30f;
;   mx = fmaxf(mx, __shfl_xor(mx, 32));
;   if (MASK == 2) mx = lanesel ? mx : -1e30f;
.Lfhs_3:
	ds_read_b128 v[244:247], v250
	s_waitcnt lgkmcnt(0)
	v_min3_u32 v248, v244, v245, v246
	v_min_u32_e32 v248, v248, v247
	v_cmp_ge_u32_e32 vcc, v248, v251
	s_cbranch_vccz .Lfhs_3
	s_waitcnt vmcnt(0) lgkmcnt(0)
	v_add3_u32 v38, s81, v161, v162
	ds_read_b128 v[0:3], v38
	ds_read_b128 v[4:7], v38 offset:32
	s_add_i32 s10, s80, 1
	s_lshl_b32 s0, s10, 6
	s_waitcnt lgkmcnt(1)
	v_mfma_f32_32x32x16_bf16 v[16:31], v[0:3], v[64:67], 0
	ds_read_b128 v[0:3], v38 offset:64
	ds_read_b128 v[34:37], v38 offset:4640
	s_cmp_lt_u32 s80, s86
	s_cselect_b32 s0, s0, 0
	s_lshl_b32 s11, s80, 10
	s_add_i32 s8, s0, s88
	s_mov_b32 s9, s18
	s_waitcnt lgkmcnt(2)
	v_mfma_f32_32x32x16_bf16 v[16:31], v[4:7], v[68:71], v[16:31]
	s_lshl_b64 s[8:9], s[8:9], 7
	s_mov_b32 s1, s18
	s_xor_b32 s79, s79, 1
	s_cmp_eq_u32 s80, s86
	s_waitcnt lgkmcnt(1)
	v_mfma_f32_32x32x16_bf16 v[16:31], v[0:3], v[72:75], v[16:31]
	ds_read_b128 v[0:3], v38 offset:96
	s_waitcnt lgkmcnt(0)
	v_mfma_f32_32x32x16_bf16 v[16:31], v[0:3], v[76:79], v[16:31]
	ds_read_b128 v[0:3], v38 offset:4608
	s_waitcnt lgkmcnt(0)
	v_mfma_f32_32x32x16_bf16 v[0:15], v[0:3], v[64:67], 0
	s_nop 8
	v_fma_f32 v16, 0, v106, v16
	v_fmamk_f32 v17, v106, 0x41800000, v17
	v_fmamk_f32 v18, v106, 0x42000000, v18
	v_fmamk_f32 v19, v106, 0x42400000, v19
	v_fmamk_f32 v20, v106, 0x43000000, v20
	v_fmamk_f32 v21, v106, 0x43100000, v21
	v_fmamk_f32 v22, v106, 0x43200000, v22
	v_mfma_f32_32x32x16_bf16 v[0:15], v[34:37], v[68:71], v[0:15]
	ds_read_b128 v[34:37], v38 offset:4672
	v_fmamk_f32 v23, v106, 0x43300000, v23
	v_fmamk_f32 v24, v106, 0x43800000, v24
	v_fmamk_f32 v25, v106, 0x43880000, v25
	v_fmamk_f32 v26, v106, 0x43900000, v26
	v_fmamk_f32 v27, v106, 0x43980000, v27
	v_fmamk_f32 v28, v106, 0x43c00000, v28
	s_waitcnt lgkmcnt(0)
	v_mfma_f32_32x32x16_bf16 v[0:15], v[34:37], v[72:75], v[0:15]
	ds_read_b128 v[34:37], v38 offset:4704
	v_fmamk_f32 v29, v106, 0x43c80000, v29
	v_fmamk_f32 v30, v106, 0x43d00000, v30
	v_fmac_f32_e32 v31, 0x43d80000, v106
	s_waitcnt lgkmcnt(0)
	v_mfma_f32_32x32x16_bf16 v[0:15], v[34:37], v[76:79], v[0:15]
	v_subrev_u32_e32 v34, s11, v135
	v_add_u32_e32 v34, v34, v136
	v_cmp_lt_i32_e32 vcc, -1, v34
	v_cvt_f32_i32_e32 v35, v34
	v_and_b32_e32 v37, 64, v101
	v_cndmask_b32_e32 v16, v160, v16, vcc
	v_cmp_lt_i32_e32 vcc, 15, v34
	s_nop 4
	v_fmamk_f32 v0, v106, 0x44000000, v0
	v_fmamk_f32 v1, v106, 0x44040000, v1
	v_cndmask_b32_e32 v17, v160, v17, vcc
	v_cmp_lt_i32_e32 vcc, 31, v34
	v_max3_f32 v36, v16, s95, v17
	v_fmamk_f32 v2, v106, 0x44080000, v2
	v_cndmask_b32_e32 v18, v160, v18, vcc
	v_cmp_lt_i32_e32 vcc, 47, v34
	v_fmamk_f32 v3, v106, 0x440c0000, v3
	v_fmamk_f32 v4, v106, 0x44200000, v4
	v_cndmask_b32_e32 v19, v160, v19, vcc
	v_cmp_lt_i32_e32 vcc, s96, v34
	v_max3_f32 v36, v36, v18, v19
	v_fmamk_f32 v5, v106, 0x44240000, v5
	v_cndmask_b32_e32 v20, v160, v20, vcc
	v_cmp_lt_i32_e32 vcc, s97, v34
	v_fmamk_f32 v6, v106, 0x44280000, v6
	v_fmamk_f32 v7, v106, 0x442c0000, v7
	v_cndmask_b32_e32 v21, v160, v21, vcc
	v_cmp_lt_i32_e32 vcc, s6, v34
	v_max3_f32 v36, v36, v20, v21
	v_fmamk_f32 v8, v106, 0x44400000, v8
	v_cndmask_b32_e32 v22, v160, v22, vcc
	v_cmp_lt_i32_e32 vcc, s7, v34
	v_fmamk_f32 v9, v106, 0x44440000, v9
	v_fmamk_f32 v10, v106, 0x44480000, v10
	v_cndmask_b32_e32 v23, v160, v23, vcc
	v_cmp_lt_i32_e32 vcc, s34, v34
	v_max3_f32 v36, v36, v22, v23
	v_fmamk_f32 v11, v106, 0x444c0000, v11
	v_cndmask_b32_e32 v24, v160, v24, vcc
	v_cmp_lt_i32_e32 vcc, s35, v34
	v_fmamk_f32 v12, v106, 0x44600000, v12
	v_fmamk_f32 v13, v106, 0x44640000, v13
	v_cndmask_b32_e32 v25, v160, v25, vcc
	v_cmp_lt_i32_e32 vcc, s14, v34
	v_max3_f32 v36, v36, v24, v25
	v_fmamk_f32 v14, v106, 0x44680000, v14
	v_cndmask_b32_e32 v26, v160, v26, vcc
	v_cmp_lt_i32_e32 vcc, s15, v34
	v_fmac_f32_e32 v15, 0x446c0000, v106
	v_add_u32_e32 v131, 64, v37
	v_cndmask_b32_e32 v27, v160, v27, vcc
	v_cmp_lt_i32_e32 vcc, s20, v34
	v_max3_f32 v36, v36, v26, v27
	s_nop 0
	v_cndmask_b32_e32 v28, v160, v28, vcc
	v_cmp_lt_i32_e32 vcc, s21, v34
	s_nop 1
	v_cndmask_b32_e32 v29, v160, v29, vcc
	v_cmp_lt_i32_e32 vcc, s2, v34
	v_max3_f32 v36, v36, v28, v29
	s_nop 0
	v_cndmask_b32_e32 v30, v160, v30, vcc
	v_cmp_lt_i32_e32 vcc, s3, v34
	s_nop 1
	v_cndmask_b32_e32 v31, v160, v31, vcc
	v_cmp_lt_i32_e32 vcc, s24, v34
	v_max3_f32 v36, v36, v30, v31
	s_nop 0
	v_cndmask_b32_e32 v0, v160, v0, vcc
	v_cmp_lt_i32_e32 vcc, s25, v34
	s_nop 1
	v_cndmask_b32_e32 v1, v160, v1, vcc
	v_cmp_lt_i32_e32 vcc, s36, v34
	v_max3_f32 v36, v36, v0, v1
	s_nop 0
	v_cndmask_b32_e32 v2, v160, v2, vcc
	v_cmp_lt_i32_e32 vcc, s37, v34
	s_nop 1
	v_cndmask_b32_e32 v3, v160, v3, vcc
	v_cmp_lt_i32_e32 vcc, s12, v34
	v_max3_f32 v36, v36, v2, v3
	s_nop 0
	v_cndmask_b32_e32 v4, v160, v4, vcc
	v_cmp_lt_i32_e32 vcc, s13, v34
	s_nop 1
	v_cndmask_b32_e32 v5, v160, v5, vcc
	v_cmp_lt_i32_e32 vcc, s22, v34
	v_max3_f32 v36, v36, v4, v5
	s_nop 0
	v_cndmask_b32_e32 v6, v160, v6, vcc
	v_cmp_lt_i32_e32 vcc, s23, v34
	s_nop 1
	v_cndmask_b32_e32 v7, v160, v7, vcc
	v_cmp_lt_i32_e32 vcc, s16, v34
	v_max3_f32 v36, v36, v6, v7
	s_nop 0
	v_cndmask_b32_e32 v8, v160, v8, vcc
	v_cmp_lt_i32_e32 vcc, s17, v34
	s_nop 1
	v_cndmask_b32_e32 v9, v160, v9, vcc
	v_cmp_lt_i32_e32 vcc, s26, v34
	v_max3_f32 v36, v36, v8, v9
	s_nop 0
	v_cndmask_b32_e32 v10, v160, v10, vcc
	v_cmp_lt_i32_e32 vcc, s27, v34
	s_nop 1
	v_cndmask_b32_e32 v11, v160, v11, vcc
	v_cmp_lt_i32_e32 vcc, s28, v34
	v_max3_f32 v36, v36, v10, v11
	s_nop 0
	v_cndmask_b32_e32 v12, v160, v12, vcc
	v_cmp_lt_i32_e32 vcc, s29, v34
	s_nop 1
	v_cndmask_b32_e32 v13, v160, v13, vcc
	v_cmp_lt_i32_e32 vcc, s30, v34
	v_max3_f32 v36, v36, v12, v13
	s_nop 0
	v_cndmask_b32_e32 v14, v160, v14, vcc
	v_cmp_lt_i32_e32 vcc, s31, v34
	s_nop 1
	v_cndmask_b32_e32 v15, v160, v15, vcc
	v_max3_f32 v34, v36, v14, v15
	v_cmp_lt_f32_e32 vcc, s76, v34
	v_fma_f32 v34, -v106, v35, v34
	v_xor_b32_e32 v36, 32, v101
	v_cndmask_b32_e32 v34, v160, v34, vcc
	v_cmp_lt_i32_e32 vcc, v36, v131
	s_nop 1
	v_cndmask_b32_e32 v36, v101, v36, vcc
	v_lshlrev_b32_e32 v163, 2, v36
	v_mov_b32_e32 v36, v34
	s_nop 1
	v_permlane32_swap_b32_e32 v36, v34
	s_nop 1
	v_cmp_lt_f32_e32 vcc, s76, v16
	s_waitcnt lgkmcnt(0)
; DI float fexp2(float x) { return __builtin_amdgcn_exp2f(x); }
; template <int KSTRIDE, bool WIN, int MASK, int MODE>
; DI void attend_tile(const u16* Ks, const u16* Vts, const bf16x8 (&qf)[4], f32x16 (&O)[2], float& m, float& l, int dbase,
;                     float slope2, bool lanesel, float invl, unsigned* imp_row, int mbase, int lr, int hh) {
;     ...
;   float mnew = m, alpha = 1.f;
;   if (MODE != 2) {
;     mnew = fmaxf(m, mx);
;     alpha = fexp2(m - mnew);
;     m = mnew;
;   }
;   float shift = mnew + ct;
;   if (MASK == 2) shift = lanesel ? shift : 1e30f;
;   float rs = 0.f;
; #pragma unroll
;   for (int kt = 0; kt < 2; ++kt)
; #pragma unroll
;     for (int e = 0; e < 16; ++e) {
;       float v = s[kt][e];
;       float pv;
;       if (MASK == 1) pv = (v > -1e29f) ? fexp2(v - shift) : 0.f;
;       else pv = fexp2(v - shift);
;       if (MODE == 2) pv *= invl;
;       s[kt][e] = pv;
;       rs += pv;
;     }
;   if (MODE != 2) l = l * alpha + rs;
;   if (MODE == 1) return;
; DI void attn_item(const Params& p, int item, char* smem) {
;     ...
;     const int cn = (c + 1 < nct) ? c + 1 : 0;
;     kv_issue(kvr, KCMP + ((size_t)(bg * 256 + 64 * cn)) * 64, 64, VCMPT + (size_t)bg * 64 * 256 + 64 * cn, 256, tid);
	v_max3_f32 v137, v33, v34, v36
	v_fma_f32 v34, v106, v35, v137
	v_sub_f32_e32 v16, v16, v34
	v_exp_f32_e32 v16, v16
	s_nop 0
	v_add_f32_e32 v16, 0, v16
	v_cndmask_b32_e32 v16, 0, v16, vcc
	v_cmp_lt_f32_e32 vcc, s76, v17
	v_sub_f32_e32 v17, v17, v34
	v_exp_f32_e32 v17, v17
	s_nop 0
	v_cndmask_b32_e32 v17, 0, v17, vcc
	v_add_f32_e32 v16, v17, v16
	v_sub_f32_e32 v17, v18, v34
	v_exp_f32_e32 v17, v17
	v_cmp_lt_f32_e32 vcc, s76, v18
	s_nop 1
	v_cndmask_b32_e32 v17, 0, v17, vcc
	v_add_f32_e32 v16, v17, v16
	v_sub_f32_e32 v17, v19, v34
	v_exp_f32_e32 v17, v17
	v_cmp_lt_f32_e32 vcc, s76, v19
	s_nop 1
	v_cndmask_b32_e32 v17, 0, v17, vcc
	v_add_f32_e32 v16, v17, v16
	v_sub_f32_e32 v17, v20, v34
	v_exp_f32_e32 v17, v17
	v_cmp_lt_f32_e32 vcc, s76, v20
	s_nop 1
	v_cndmask_b32_e32 v17, 0, v17, vcc
	v_add_f32_e32 v16, v17, v16
	v_sub_f32_e32 v17, v21, v34
	v_exp_f32_e32 v17, v17
	v_cmp_lt_f32_e32 vcc, s76, v21
	s_nop 1
	v_cndmask_b32_e32 v17, 0, v17, vcc
	v_add_f32_e32 v16, v17, v16
	v_sub_f32_e32 v17, v22, v34
	v_exp_f32_e32 v17, v17
	v_cmp_lt_f32_e32 vcc, s76, v22
	s_nop 1
	v_cndmask_b32_e32 v17, 0, v17, vcc
	v_add_f32_e32 v16, v17, v16
	v_sub_f32_e32 v17, v23, v34
	v_exp_f32_e32 v17, v17
	v_cmp_lt_f32_e32 vcc, s76, v23
	s_nop 1
	v_cndmask_b32_e32 v17, 0, v17, vcc
	v_add_f32_e32 v16, v17, v16
	v_sub_f32_e32 v17, v24, v34
	v_exp_f32_e32 v17, v17
	v_cmp_lt_f32_e32 vcc, s76, v24
	s_nop 1
	v_cndmask_b32_e32 v17, 0, v17, vcc
	v_add_f32_e32 v16, v17, v16
	v_sub_f32_e32 v17, v25, v34
	v_exp_f32_e32 v17, v17
	v_cmp_lt_f32_e32 vcc, s76, v25
	s_nop 1
	v_cndmask_b32_e32 v17, 0, v17, vcc
	v_add_f32_e32 v16, v17, v16
	v_sub_f32_e32 v17, v26, v34
	v_exp_f32_e32 v17, v17
	v_cmp_lt_f32_e32 vcc, s76, v26
	s_nop 1
	v_cndmask_b32_e32 v17, 0, v17, vcc
	v_add_f32_e32 v16, v17, v16
	v_sub_f32_e32 v17, v27, v34
	v_exp_f32_e32 v17, v17
	v_cmp_lt_f32_e32 vcc, s76, v27
	s_nop 1
	v_cndmask_b32_e32 v17, 0, v17, vcc
	v_add_f32_e32 v16, v17, v16
	v_sub_f32_e32 v17, v28, v34
	v_exp_f32_e32 v17, v17
	v_cmp_lt_f32_e32 vcc, s76, v28
	s_nop 1
	v_cndmask_b32_e32 v17, 0, v17, vcc
	v_add_f32_e32 v16, v17, v16
	v_sub_f32_e32 v17, v29, v34
	v_exp_f32_e32 v17, v17
	v_cmp_lt_f32_e32 vcc, s76, v29
	s_nop 1
	v_cndmask_b32_e32 v17, 0, v17, vcc
	v_add_f32_e32 v16, v17, v16
	v_sub_f32_e32 v17, v30, v34
	v_exp_f32_e32 v17, v17
	v_cmp_lt_f32_e32 vcc, s76, v30
	s_nop 1
	v_cndmask_b32_e32 v17, 0, v17, vcc
	v_add_f32_e32 v16, v17, v16
	v_sub_f32_e32 v17, v31, v34
	v_exp_f32_e32 v17, v17
	v_cmp_lt_f32_e32 vcc, s76, v31
	s_nop 1
	v_cndmask_b32_e32 v17, 0, v17, vcc
	v_cmp_lt_f32_e32 vcc, s76, v0
	v_sub_f32_e32 v0, v0, v34
	v_exp_f32_e32 v0, v0
	v_add_f32_e32 v16, v17, v16
	v_cndmask_b32_e32 v0, 0, v0, vcc
	v_cmp_lt_f32_e32 vcc, s76, v1
	v_sub_f32_e32 v1, v1, v34
	v_exp_f32_e32 v1, v1
	v_add_f32_e32 v0, v0, v16
	v_cndmask_b32_e32 v1, 0, v1, vcc
	v_add_f32_e32 v0, v1, v0
	v_sub_f32_e32 v1, v2, v34
	v_exp_f32_e32 v1, v1
	v_cmp_lt_f32_e32 vcc, s76, v2
	s_nop 1
	v_cndmask_b32_e32 v1, 0, v1, vcc
	v_add_f32_e32 v0, v1, v0
	v_sub_f32_e32 v1, v3, v34
	v_exp_f32_e32 v1, v1
	v_cmp_lt_f32_e32 vcc, s76, v3
	v_lshl_add_u64 v[2:3], v[122:123], 0, s[8:9]
	s_nop 0
	v_cndmask_b32_e32 v1, 0, v1, vcc
	v_add_f32_e32 v0, v1, v0
	v_sub_f32_e32 v1, v4, v34
	v_exp_f32_e32 v1, v1
	v_cmp_lt_f32_e32 vcc, s76, v4
	s_nop 1
	v_cndmask_b32_e32 v1, 0, v1, vcc
	v_add_f32_e32 v0, v1, v0
	v_cmp_lt_f32_e32 vcc, s76, v5
	v_sub_f32_e32 v1, v5, v34
	v_lshl_add_u64 v[4:5], v[118:119], 1, v[2:3]
	v_lshl_add_u64 v[2:3], v[120:121], 1, v[2:3]
	global_load_dwordx4 v[80:83], v[4:5], off
	global_load_dwordx4 v[88:91], v[2:3], off
	v_lshl_add_u64 v[2:3], s[0:1], 1, v[116:117]
	v_lshl_add_u64 v[4:5], v[108:109], 1, v[2:3]
	v_lshl_add_u64 v[2:3], v[110:111], 1, v[2:3]
	global_load_dwordx4 v[84:87], v[4:5], off
	global_load_dwordx4 v[92:95], v[2:3], off
	v_exp_f32_e32 v1, v1
	s_nop 0
	v_cndmask_b32_e32 v1, 0, v1, vcc
	v_add_f32_e32 v0, v1, v0
	v_sub_f32_e32 v1, v6, v34
	v_exp_f32_e32 v1, v1
	v_cmp_lt_f32_e32 vcc, s76, v6
	s_nop 1
	v_cndmask_b32_e32 v1, 0, v1, vcc
	v_add_f32_e32 v0, v1, v0
	v_sub_f32_e32 v1, v7, v34
	v_exp_f32_e32 v1, v1
	v_cmp_lt_f32_e32 vcc, s76, v7
	s_nop 1
	v_cndmask_b32_e32 v1, 0, v1, vcc
	v_add_f32_e32 v0, v1, v0
	v_sub_f32_e32 v1, v8, v34
	v_exp_f32_e32 v1, v1
	v_cmp_lt_f32_e32 vcc, s76, v8
	s_nop 1
	v_cndmask_b32_e32 v1, 0, v1, vcc
	v_add_f32_e32 v0, v1, v0
	v_sub_f32_e32 v1, v9, v34
	v_exp_f32_e32 v1, v1
	v_cmp_lt_f32_e32 vcc, s76, v9
	s_nop 1
	v_cndmask_b32_e32 v1, 0, v1, vcc
	v_add_f32_e32 v0, v1, v0
	v_sub_f32_e32 v1, v10, v34
	v_exp_f32_e32 v1, v1
	v_cmp_lt_f32_e32 vcc, s76, v10
	s_nop 1
	v_cndmask_b32_e32 v1, 0, v1, vcc
	v_add_f32_e32 v0, v1, v0
	v_sub_f32_e32 v1, v11, v34
	v_exp_f32_e32 v1, v1
	v_cmp_lt_f32_e32 vcc, s76, v11
	s_nop 1
	v_cndmask_b32_e32 v1, 0, v1, vcc
	v_add_f32_e32 v0, v1, v0
	v_sub_f32_e32 v1, v12, v34
	v_exp_f32_e32 v1, v1
	v_cmp_lt_f32_e32 vcc, s76, v12
	s_nop 1
	v_cndmask_b32_e32 v1, 0, v1, vcc
	v_add_f32_e32 v0, v1, v0
	v_sub_f32_e32 v1, v13, v34
	v_exp_f32_e32 v1, v1
	v_cmp_lt_f32_e32 vcc, s76, v13
	s_nop 1
	v_cndmask_b32_e32 v1, 0, v1, vcc
	v_add_f32_e32 v0, v1, v0
	v_sub_f32_e32 v1, v14, v34
	v_exp_f32_e32 v1, v1
	v_cmp_lt_f32_e32 vcc, s76, v14
	s_nop 1
	v_cndmask_b32_e32 v1, 0, v1, vcc
	v_add_f32_e32 v0, v1, v0
	v_sub_f32_e32 v1, v15, v34
	v_exp_f32_e32 v1, v1
	v_cmp_lt_f32_e32 vcc, s76, v15
	s_nop 1
	v_cndmask_b32_e32 v1, 0, v1, vcc
	v_add_f32_e32 v1, v1, v0
	v_sub_f32_e32 v0, v33, v137
	v_exp_f32_e32 v0, v0
	s_nop 0
	v_fmac_f32_e32 v1, v32, v0
	s_cbranch_scc1 .LBB0_558
	v_mov_b32_e32 v32, v1
	s_mov_b32 s80, s10
	v_mov_b32_e32 v33, v137
	s_branch .LBB0_547

; #define MFMA32(a, b, c) __builtin_amdgcn_mfma_f32_32x32x16_bf16((a), (b), (c), 0, 0, 0)
; DI float fexp2(float x) { return __builtin_amdgcn_exp2f(x); }
; template <int KSTRIDE, bool WIN, int MASK, int MODE>
; DI void attend_tile(const u16* Ks, const u16* Vts, const bf16x8 (&qf)[4], f32x16 (&O)[2], float& m, float& l, int dbase,
;                     float slope2, bool lanesel, float invl, unsigned* imp_row, int mbase, int lr, int hh) {
;   f32x16 s[2];
; #pragma unroll
;   for (int kt = 0; kt < 2; ++kt) {
; #pragma unroll
;     for (int e = 0; e < 16; ++e) s[kt][e] = 0.f;
; #pragma unroll
;     for (int ks = 0; ks < 4; ++ks) {
;       bf16x8 a = *(const bf16x8*)(Ks + (kt * 32 + lr) * 72 + ks * 16 + hh * 8);
;       s[kt] = MFMA32(a, qf[ks], s[kt]);
;     }
;   }
;   const float fd0 = (float)(dbase - KSTRIDE * 4 * hh);
;   const float ct = slope2 * fd0;
;   float mx = -1e30f;
; #pragma unroll
;   for (int kt = 0; kt < 2; ++kt)
; #pragma unroll
;     for (int e = 0; e < 16; ++e) {
;       const float Ke = (float)(KSTRIDE * (kt * 32 + (e & 3) + 8 * (e >> 2)));
;       float v = fmaf(slope2, Ke, s[kt][e]);
;       if (MASK == 1) {
;         const float fd = fd0 - Ke;
;         bool valid = fd >= 0.f;
;         if (WIN) valid = valid && (fd < 512.f);
;         valid = valid && lanesel;
;         v = valid ? v : -1e30f;
;       }
;       s[kt][e] = v;
;       mx = fmaxf(mx, v);
;     }
;   mx = (mx > -1e29f) ? mx - ct : -1e30f;
;   mx = fmaxf(mx, __shfl_xor(mx, 32));
;   if (MASK == 2) mx = lanesel ? mx : -1e30f;
;   float mnew = m, alpha = 1.f;
;   if (MODE != 2) {
;     mnew = fmaxf(m, mx);
;     alpha = fexp2(m - mnew);
;     m = mnew;
;   }
;   float shift = mnew + ct;
;   if (MASK == 2) shift = lanesel ? shift : 1e30f;
;   float rs = 0.f;
; #pragma unroll
;   for (int kt = 0; kt < 2; ++kt)
; #pragma unroll
;     for (int e = 0; e < 16; ++e) {
;       float v = s[kt][e];
;       float pv;
;       if (MASK == 1) pv = (v > -1e29f) ? fexp2(v - shift) : 0.f;
;       else pv = fexp2(v - shift);
;       if (MODE == 2) pv *= invl;
;       s[kt][e] = pv;
;       rs += pv;
;     }
;   if (MODE != 2) l = l * alpha + rs;
;   if (MODE == 1) return;
;   if (MODE == 0) {
; #pragma unroll
;     for (int e = 0; e < 16; ++e) { O[0][e] *= alpha; O[1][e] *= alpha; }
.LBB0_623:
	v_add3_u32 v144, s38, v161, v162
	s_waitcnt lgkmcnt(8)
	ds_read_b128 v[80:83], v144
	s_waitcnt lgkmcnt(8)
	ds_read_b128 v[60:63], v144 offset:32
	s_waitcnt lgkmcnt(8)
	ds_read_b128 v[56:59], v144 offset:64
	s_waitcnt lgkmcnt(8)
	ds_read_b128 v[48:51], v144 offset:96
	s_waitcnt lgkmcnt(8)
	ds_read_b128 v[52:55], v144 offset:4608
	s_and_b32 s0, s89, 7
	s_cmp_eq_u32 s0, 0
	s_cbranch_scc1 .LBB0_628
	s_waitcnt lgkmcnt(4)
	v_mfma_f32_32x32x16_bf16 v[16:31], v[80:83], v[64:67], 0
	ds_read_b128 v[84:87], v144 offset:4640
	ds_read_b128 v[146:149], v144 offset:4672
	s_waitcnt lgkmcnt(5)
	v_mfma_f32_32x32x16_bf16 v[16:31], v[60:63], v[68:71], v[16:31]
	s_waitcnt lgkmcnt(2)
	v_mfma_f32_32x32x16_bf16 v[0:15], v[52:55], v[64:67], 0
	v_mfma_f32_32x32x16_bf16 v[16:31], v[56:59], v[72:75], v[16:31]
	s_waitcnt lgkmcnt(1)
	v_mfma_f32_32x32x16_bf16 v[0:15], v[84:87], v[68:71], v[0:15]
	ds_read_b128 v[84:87], v144 offset:4704
	v_mfma_f32_32x32x16_bf16 v[16:31], v[48:51], v[76:79], v[16:31]
	s_waitcnt lgkmcnt(1)
	v_mfma_f32_32x32x16_bf16 v[0:15], v[146:149], v[72:75], v[0:15]
	s_nop 9
	v_fma_f32 v16, 0, v106, v16
	v_add_f32_e32 v17, v106, v17
	v_fma_f32 v18, 2.0, v106, v18
	v_fmamk_f32 v19, v106, 0x40400000, v19
	v_fmamk_f32 v20, v106, 0x41000000, v20
	v_fmamk_f32 v21, v106, 0x41100000, v21
	v_fmamk_f32 v22, v106, 0x41200000, v22
	s_waitcnt lgkmcnt(0)
	v_mfma_f32_32x32x16_bf16 v[0:15], v[84:87], v[76:79], v[0:15]
	v_max3_f32 v85, v16, s95, v17
	v_max3_f32 v85, v85, v18, v19
	v_max3_f32 v85, v85, v20, v21
	v_fmamk_f32 v23, v106, 0x41300000, v23
	v_max3_f32 v85, v85, v22, v23
	v_fmamk_f32 v24, v106, 0x41800000, v24
	v_fmamk_f32 v25, v106, 0x41880000, v25
	v_max3_f32 v85, v85, v24, v25
	v_fmamk_f32 v26, v106, 0x41900000, v26
	v_fmamk_f32 v27, v106, 0x41980000, v27
	v_max3_f32 v85, v85, v26, v27
	v_fmamk_f32 v28, v106, 0x41c00000, v28
	v_fmamk_f32 v29, v106, 0x41c80000, v29
	v_max3_f32 v85, v85, v28, v29
	v_fmamk_f32 v30, v106, 0x41d00000, v30
	v_fmac_f32_e32 v31, 0x41d80000, v106
	v_max3_f32 v85, v85, v30, v31
	v_fmamk_f32 v0, v106, 0x42000000, v0
	v_fmamk_f32 v1, v106, 0x42040000, v1
	v_max3_f32 v85, v85, v0, v1
	v_fmamk_f32 v2, v106, 0x42080000, v2
	v_fmamk_f32 v3, v106, 0x420c0000, v3
	v_max3_f32 v85, v85, v2, v3
	v_fmamk_f32 v4, v106, 0x42200000, v4
	v_fmamk_f32 v5, v106, 0x42240000, v5
	v_or_b32_e32 v84, s8, v116
	v_max3_f32 v85, v85, v4, v5
	v_fmamk_f32 v6, v106, 0x42280000, v6
	v_fmamk_f32 v7, v106, 0x422c0000, v7
	v_sub_u32_e32 v84, v157, v84
	v_max3_f32 v85, v85, v6, v7
	v_fmamk_f32 v8, v106, 0x42400000, v8
	v_fmamk_f32 v9, v106, 0x42440000, v9
	v_cvt_f32_i32_e32 v84, v84
	v_max3_f32 v85, v85, v8, v9
	v_fmamk_f32 v10, v106, 0x42480000, v10
	v_fmamk_f32 v11, v106, 0x424c0000, v11
	v_max3_f32 v85, v85, v10, v11
	v_fmamk_f32 v12, v106, 0x42600000, v12
	v_fmamk_f32 v13, v106, 0x42640000, v13
	v_max3_f32 v85, v85, v12, v13
	v_fmamk_f32 v14, v106, 0x42680000, v14
	v_fmac_f32_e32 v15, 0x426c0000, v106
	v_max3_f32 v85, v85, v14, v15
	v_cmp_lt_f32_e32 vcc, s76, v85
	v_fma_f32 v85, -v106, v84, v85
	s_nop 0
	v_cndmask_b32_e32 v85, v160, v85, vcc
	v_mov_b32_e32 v86, v85
	s_nop 1
	v_permlane32_swap_b32_e32 v86, v85
	s_nop 1
	s_waitcnt lgkmcnt(0)
	v_max3_f32 v145, v143, v85, v86
	v_fma_f32 v84, v106, v84, v145
	v_sub_f32_e32 v16, v16, v84
	v_exp_f32_e32 v86, v16
	v_sub_f32_e32 v17, v17, v84
	v_exp_f32_e32 v87, v17
	v_sub_f32_e32 v17, v18, v84
	v_exp_f32_e32 v181, v17
	v_sub_f32_e32 v17, v19, v84
	v_exp_f32_e32 v182, v17
	v_sub_f32_e32 v17, v20, v84
	v_add_f32_e32 v16, 0, v86
	v_exp_f32_e32 v183, v17
	v_sub_f32_e32 v17, v21, v84
	v_add_f32_e32 v16, v87, v16
	v_exp_f32_e32 v184, v17
	v_sub_f32_e32 v17, v22, v84
	v_sub_f32_e32 v1, v1, v84
	v_add_f32_e32 v16, v181, v16
	v_exp_f32_e32 v185, v17
	v_sub_f32_e32 v17, v23, v84
	v_exp_f32_e32 v148, v1
	v_sub_f32_e32 v1, v2, v84
	v_add_f32_e32 v16, v182, v16
	v_exp_f32_e32 v186, v17
	v_sub_f32_e32 v17, v24, v84
	v_exp_f32_e32 v149, v1
	v_sub_f32_e32 v1, v3, v84
	v_add_f32_e32 v16, v183, v16
	v_exp_f32_e32 v172, v17
	v_sub_f32_e32 v17, v25, v84
	v_exp_f32_e32 v150, v1
	v_sub_f32_e32 v1, v4, v84
	v_add_f32_e32 v16, v184, v16
	v_exp_f32_e32 v174, v17
	v_sub_f32_e32 v17, v26, v84
	v_exp_f32_e32 v151, v1
	v_sub_f32_e32 v1, v5, v84
	v_add_f32_e32 v16, v185, v16
	v_exp_f32_e32 v175, v17
	v_sub_f32_e32 v17, v27, v84
	v_exp_f32_e32 v152, v1
	v_sub_f32_e32 v1, v6, v84
	v_add_f32_e32 v16, v186, v16
	v_exp_f32_e32 v176, v17
	v_sub_f32_e32 v17, v28, v84
	v_exp_f32_e32 v153, v1
	v_sub_f32_e32 v1, v7, v84
	v_add_f32_e32 v16, v172, v16
	v_exp_f32_e32 v177, v17
	v_sub_f32_e32 v17, v29, v84
	v_exp_f32_e32 v165, v1
	v_sub_f32_e32 v1, v8, v84
	v_add_f32_e32 v16, v174, v16
	v_exp_f32_e32 v178, v17
	v_sub_f32_e32 v17, v30, v84
	v_exp_f32_e32 v164, v1
	v_sub_f32_e32 v1, v9, v84
	v_add_f32_e32 v16, v175, v16
	v_exp_f32_e32 v179, v17
	v_sub_f32_e32 v17, v31, v84
	v_exp_f32_e32 v166, v1
	v_sub_f32_e32 v1, v10, v84
	v_add_f32_e32 v16, v176, v16
	v_exp_f32_e32 v180, v17
	v_sub_f32_e32 v0, v0, v84
	v_exp_f32_e32 v167, v1
	v_sub_f32_e32 v1, v11, v84
	v_add_f32_e32 v16, v177, v16
	v_exp_f32_e32 v147, v0
	v_exp_f32_e32 v168, v1
	v_sub_f32_e32 v1, v12, v84
	v_add_f32_e32 v16, v178, v16
	v_exp_f32_e32 v169, v1
	v_sub_f32_e32 v1, v13, v84
	v_sub_f32_e32 v85, v143, v145
	v_add_f32_e32 v16, v179, v16
	v_exp_f32_e32 v170, v1
	v_sub_f32_e32 v1, v14, v84
	v_add_f32_e32 v16, v180, v16
	v_exp_f32_e32 v171, v1
	v_sub_f32_e32 v1, v15, v84
	v_exp_f32_e32 v14, v85
	v_cvt_pk_bf16_f32 v84, v86, v87
	v_cvt_pk_bf16_f32 v85, v181, v182
	v_cvt_pk_bf16_f32 v86, v183, v184
	v_cvt_pk_bf16_f32 v87, v185, v186
	ds_read_b128 v[182:185], v144 offset:9216
	v_add_f32_e32 v0, v147, v16
	v_add_f32_e32 v0, v148, v0
	v_add_f32_e32 v0, v149, v0
	v_add_f32_e32 v0, v150, v0
	v_add_f32_e32 v0, v151, v0
	v_add_f32_e32 v0, v152, v0
	v_add_f32_e32 v0, v153, v0
	v_add_f32_e32 v0, v165, v0
	v_pk_mul_f32 v[16:17], v[108:109], v[14:15] op_sel_hi:[1,0]
	v_pk_mul_f32 v[18:19], v[110:111], v[14:15] op_sel_hi:[1,0]
	v_pk_mul_f32 v[20:21], v[112:113], v[14:15] op_sel_hi:[1,0]
	v_pk_mul_f32 v[22:23], v[114:115], v[14:15] op_sel_hi:[1,0]
	v_pk_mul_f32 v[24:25], v[118:119], v[14:15] op_sel_hi:[1,0]
	v_pk_mul_f32 v[26:27], v[120:121], v[14:15] op_sel_hi:[1,0]
	v_pk_mul_f32 v[28:29], v[122:123], v[14:15] op_sel_hi:[1,0]
	v_pk_mul_f32 v[30:31], v[124:125], v[14:15] op_sel_hi:[1,0]
	v_add_f32_e32 v0, v164, v0
	v_add_f32_e32 v0, v166, v0
	s_waitcnt lgkmcnt(0)
; #define MFMA32(a, b, c) __builtin_amdgcn_mfma_f32_32x32x16_bf16((a), (b), (c), 0, 0, 0)
; template <int KSTRIDE, bool WIN, int MASK, int MODE>
; DI void attend_tile(const u16* Ks, const u16* Vts, const bf16x8 (&qf)[4], f32x16 (&O)[2], float& m, float& l, int dbase,
;                     float slope2, bool lanesel, float invl, unsigned* imp_row, int mbase, int lr, int hh) {
;   f32x16 s[2];
; #pragma unroll
;   for (int kt = 0; kt < 2; ++kt) {
; #pragma unroll
;     for (int e = 0; e < 16; ++e) s[kt][e] = 0.f;
; #pragma unroll
;     for (int ks = 0; ks < 4; ++ks) {
;       bf16x8 a = *(const bf16x8*)(Ks + (kt * 32 + lr) * 72 + ks * 16 + hh * 8);
;       s[kt] = MFMA32(a, qf[ks], s[kt]);
;     }
;   }
;   const float fd0 = (float)(dbase - KSTRIDE * 4 * hh);
;   const float ct = slope2 * fd0;
;   float mx = -1e30f;
; #pragma unroll
;   for (int kt = 0; kt < 2; ++kt)
; #pragma unroll
;     for (int e = 0; e < 16; ++e) {
;       const float Ke = (float)(KSTRIDE * (kt * 32 + (e & 3) + 8 * (e >> 2)));
;       float v = fmaf(slope2, Ke, s[kt][e]);
;       if (MASK == 1) {
;         const float fd = fd0 - Ke;
;         bool valid = fd >= 0.f;
;         if (WIN) valid = valid && (fd < 512.f);
;         valid = valid && lanesel;
;         v = valid ? v : -1e30f;
;       }
;       s[kt][e] = v;
;       mx = fmaxf(mx, v);
;     }
;     ...
; #pragma unroll
;   for (int kt = 0; kt < 2; ++kt)
; #pragma unroll
;     for (int sx = 0; sx < 2; ++sx) {
;       unsigned pk[4];
; #pragma unroll
;       for (int q = 0; q < 4; ++q) pk[q] = pack2(s[kt][8 * sx + 2 * q], s[kt][8 * sx + 2 * q + 1]);
;       bf16x8 pb;
;       {
;         u32x4 t4 = {pk[0], pk[1], pk[2], pk[3]};
;         pb = __builtin_bit_cast(bf16x8, t4);
;       }
; #pragma unroll
;       for (int dt = 0; dt < 2; ++dt) {
;         bf16x8 a = *(const bf16x8*)(Vts + (dt * 32 + lr) * 72 + kt * 32 + 16 * sx + 8 * hh);
;         O[dt] = MFMA32(a, pb, O[dt]);
;       }
;     }
	v_mfma_f32_32x32x16_bf16 v[16:31], v[182:185], v[84:87], v[16:31]
	ds_read_b128 v[182:185], v144 offset:13824
	v_add_f32_e32 v0, v167, v0
	v_add_f32_e32 v0, v168, v0
	v_exp_f32_e32 v173, v1
	v_add_f32_e32 v0, v169, v0
	v_add_f32_e32 v0, v170, v0
	v_add_f32_e32 v0, v171, v0
	v_add_f32_e32 v146, v173, v0
	v_fmac_f32_e32 v146, v142, v14
	v_pk_mul_f32 v[0:1], v[132:133], v[14:15] op_sel_hi:[1,0]
	v_pk_mul_f32 v[2:3], v[134:135], v[14:15] op_sel_hi:[1,0]
	v_pk_mul_f32 v[4:5], v[138:139], v[14:15] op_sel_hi:[1,0]
	v_pk_mul_f32 v[6:7], v[126:127], v[14:15] op_sel_hi:[1,0]
	v_pk_mul_f32 v[8:9], v[128:129], v[14:15] op_sel_hi:[1,0]
	v_pk_mul_f32 v[10:11], v[130:131], v[14:15] op_sel_hi:[1,0]
	v_pk_mul_f32 v[12:13], v[136:137], v[14:15] op_sel_hi:[1,0]
	v_pk_mul_f32 v[14:15], v[140:141], v[14:15] op_sel_hi:[1,0]
	s_waitcnt lgkmcnt(0)
	s_nop 0
	v_mfma_f32_32x32x16_bf16 v[0:15], v[182:185], v[84:87], v[0:15]
	v_cvt_pk_bf16_f32 v84, v172, v174
	v_cvt_pk_bf16_f32 v85, v175, v176
	v_cvt_pk_bf16_f32 v86, v177, v178
	ds_read_b128 v[174:177], v144 offset:9248
	v_cvt_pk_bf16_f32 v87, v179, v180
	s_waitcnt lgkmcnt(0)
	s_nop 0
	v_mfma_f32_32x32x16_bf16 v[16:31], v[174:177], v[84:87], v[16:31]
	ds_read_b128 v[174:177], v144 offset:13856
	s_waitcnt lgkmcnt(0)
	v_mfma_f32_32x32x16_bf16 v[0:15], v[174:177], v[84:87], v[0:15]
	v_cvt_pk_bf16_f32 v84, v147, v148
	v_cvt_pk_bf16_f32 v85, v149, v150
	v_cvt_pk_bf16_f32 v86, v151, v152
	ds_read_b128 v[148:151], v144 offset:9280
	v_cvt_pk_bf16_f32 v87, v153, v165
	s_waitcnt lgkmcnt(0)
	s_nop 0
	v_mfma_f32_32x32x16_bf16 v[16:31], v[148:151], v[84:87], v[16:31]
	ds_read_b128 v[148:151], v144 offset:13888
	s_waitcnt lgkmcnt(0)
	v_mfma_f32_32x32x16_bf16 v[0:15], v[148:151], v[84:87], v[0:15]
	ds_read_b128 v[148:151], v144 offset:9312
	v_cvt_pk_bf16_f32 v84, v164, v166
	v_cvt_pk_bf16_f32 v85, v167, v168
	v_cvt_pk_bf16_f32 v86, v169, v170
	v_cvt_pk_bf16_f32 v87, v171, v173
	s_waitcnt lgkmcnt(0)
	s_nop 0
	v_mfma_f32_32x32x16_bf16 v[16:31], v[148:151], v[84:87], v[16:31]
	ds_read_b128 v[148:151], v144 offset:13920
	s_waitcnt lgkmcnt(0)
	v_mfma_f32_32x32x16_bf16 v[0:15], v[148:151], v[84:87], v[0:15]
	s_cbranch_execnz .LBB0_626
.LBB0_625:
	s_waitcnt lgkmcnt(4)
	v_mfma_f32_32x32x16_bf16 v[0:15], v[80:83], v[64:67], 0
	s_movk_i32 s0, 0x200
	s_mov_b32 s86, s85
	s_mov_b32 s38, s84
	s_mov_b32 s82, s19
	s_waitcnt lgkmcnt(3)
	v_mfma_f32_32x32x16_bf16 v[0:15], v[60:63], v[68:71], v[0:15]
	s_waitcnt lgkmcnt(2)
	v_mfma_f32_32x32x16_bf16 v[0:15], v[56:59], v[72:75], v[0:15]
	s_waitcnt lgkmcnt(0)
	v_mfma_f32_32x32x16_bf16 v[16:31], v[52:55], v[64:67], 0
	v_mfma_f32_32x32x16_bf16 v[0:15], v[48:51], v[76:79], v[0:15]
	ds_read_b128 v[48:51], v144 offset:4640
	ds_read_b128 v[56:59], v144 offset:4672
	s_waitcnt lgkmcnt(1)
	v_mfma_f32_32x32x16_bf16 v[16:31], v[48:51], v[68:71], v[16:31]
	ds_read_b128 v[50:53], v144 offset:4704
	v_or_b32_e32 v48, s8, v116
	v_sub_u32_e32 v49, v157, v48
	v_cvt_f32_i32_e32 v48, v49
	s_nop 3
	v_fma_f32 v0, 0, v106, v0
	v_cmp_gt_u32_e32 vcc, s0, v49
	v_pk_fma_f32 v[8:9], v[106:107], s[82:83], v[8:9]
	s_waitcnt lgkmcnt(1)
	v_mfma_f32_32x32x16_bf16 v[16:31], v[56:59], v[72:75], v[16:31]
	v_cndmask_b32_e32 v55, v160, v0, vcc
	v_add_f32_e32 v0, v106, v1
	v_add_f32_e32 v1, -1.0, v48
	v_cmp_le_f32_e32 vcc, 0, v1
	v_cmp_gt_f32_e64 s[0:1], s52, v1
	s_and_b64 vcc, vcc, s[0:1]
	s_mov_b32 s0, 0x42680000
	s_waitcnt lgkmcnt(0)
	v_mfma_f32_32x32x16_bf16 v[16:31], v[50:53], v[76:79], v[16:31]
	s_mov_b32 s1, 0x426c0000
	v_cndmask_b32_e32 v56, v160, v0, vcc
	v_fma_f32 v6, v106, s58, v6
	v_fma_f32 v7, v107, s59, v7
	v_max3_f32 v57, v55, s95, v56
	s_nop 6
	v_pk_fma_f32 v[0:1], v[106:107], s[0:1], v[30:31]
	s_mov_b32 s0, 0xc2680000
	s_mov_b32 s1, 0xc26c0000
	v_pk_add_f32 v[30:31], v[48:49], s[0:1] op_sel_hi:[0,1]
	v_cmp_le_f32_e32 vcc, 0, v31
	v_cmp_gt_f32_e64 s[8:9], s52, v31
	v_cmp_le_f32_e64 s[0:1], 0, v30
	v_cmp_gt_f32_e64 s[10:11], s52, v30
	s_and_b64 vcc, vcc, s[8:9]
	v_cndmask_b32_e32 v50, v160, v1, vcc
	s_and_b64 vcc, s[0:1], s[10:11]
	s_mov_b32 s0, 0x42600000
	s_mov_b32 s1, 0x42640000
	v_cndmask_b32_e32 v49, v160, v0, vcc
	v_pk_fma_f32 v[0:1], v[106:107], s[0:1], v[28:29]
	s_mov_b32 s0, 0xc2600000
	s_mov_b32 s1, 0xc2640000
	v_pk_add_f32 v[28:29], v[48:49], s[0:1] op_sel_hi:[0,1]
	v_cmp_le_f32_e32 vcc, 0, v29
	v_cmp_gt_f32_e64 s[8:9], s52, v29
	v_cmp_le_f32_e64 s[0:1], 0, v28
	v_cmp_gt_f32_e64 s[10:11], s52, v28
	s_and_b64 vcc, vcc, s[8:9]
	v_cndmask_b32_e32 v52, v160, v1, vcc
	s_and_b64 vcc, s[0:1], s[10:11]
	s_mov_b32 s0, 0x42480000
	s_mov_b32 s1, 0x424c0000
	v_cndmask_b32_e32 v51, v160, v0, vcc
	v_pk_fma_f32 v[0:1], v[106:107], s[0:1], v[26:27]
	s_mov_b32 s0, 0xc2480000
	s_mov_b32 s1, 0xc24c0000
	v_pk_add_f32 v[26:27], v[48:49], s[0:1] op_sel_hi:[0,1]
	v_cmp_le_f32_e32 vcc, 0, v27
	v_cmp_gt_f32_e64 s[8:9], s52, v27
	v_cmp_le_f32_e64 s[0:1], 0, v26
	v_cmp_gt_f32_e64 s[10:11], s52, v26
	s_and_b64 vcc, vcc, s[8:9]
	v_cndmask_b32_e32 v53, v160, v1, vcc
	s_and_b64 vcc, s[0:1], s[10:11]
	s_mov_b32 s0, 0xc2400000
	s_mov_b32 s1, 0xc2440000
	v_cndmask_b32_e32 v54, v160, v0, vcc
	v_pk_add_f32 v[0:1], v[48:49], s[0:1] op_sel_hi:[0,1]
	v_cmp_le_f32_e32 vcc, 0, v1
	v_cmp_gt_f32_e64 s[8:9], s52, v1
	v_pk_fma_f32 v[24:25], v[106:107], s[86:87], v[24:25]
	v_cmp_le_f32_e64 s[0:1], 0, v0
	v_cmp_gt_f32_e64 s[10:11], s52, v0
	s_and_b64 vcc, vcc, s[8:9]
	v_cndmask_b32_e32 v0, v160, v25, vcc
	s_and_b64 vcc, s[0:1], s[10:11]
	s_mov_b32 s0, 0x42280000
	s_mov_b32 s1, 0x422c0000
	v_cndmask_b32_e32 v1, v160, v24, vcc
	v_pk_fma_f32 v[24:25], v[106:107], s[0:1], v[22:23]
	s_mov_b32 s0, 0xc2280000
	s_mov_b32 s1, 0xc22c0000
	v_pk_add_f32 v[22:23], v[48:49], s[0:1] op_sel_hi:[0,1]
; template <int KSTRIDE, bool WIN, int MASK, int MODE>
; DI void attend_tile(const u16* Ks, const u16* Vts, const bf16x8 (&qf)[4], f32x16 (&O)[2], float& m, float& l, int dbase,
;                     float slope2, bool lanesel, float invl, unsigned* imp_row, int mbase, int lr, int hh) {
;     ...
;   for (int kt = 0; kt < 2; ++kt)
; #pragma unroll
;     for (int e = 0; e < 16; ++e) {
;       const float Ke = (float)(KSTRIDE * (kt * 32 + (e & 3) + 8 * (e >> 2)));
;       float v = fmaf(slope2, Ke, s[kt][e]);
;       if (MASK == 1) {
;         const float fd = fd0 - Ke;
;         bool valid = fd >= 0.f;
;         if (WIN) valid = valid && (fd < 512.f);
;         valid = valid && lanesel;
;         v = valid ? v : -1e30f;
;       }
;       s[kt][e] = v;
;       mx = fmaxf(mx, v);
;     }
;   mx = (mx > -1e29f) ? mx - ct : -1e30f;
;   mx = fmaxf(mx, __shfl_xor(mx, 32));
;   if (MASK == 2) mx = lanesel ? mx : -1e30f;
	v_cmp_le_f32_e32 vcc, 0, v23
	v_cmp_gt_f32_e64 s[8:9], s52, v23
	v_cmp_le_f32_e64 s[0:1], 0, v22
	v_cmp_gt_f32_e64 s[10:11], s52, v22
	s_and_b64 vcc, vcc, s[8:9]
	v_cndmask_b32_e32 v22, v160, v25, vcc
	s_and_b64 vcc, s[0:1], s[10:11]
	s_mov_b32 s0, 0x42200000
	s_mov_b32 s1, 0x42240000
	v_cndmask_b32_e32 v23, v160, v24, vcc
	v_pk_fma_f32 v[24:25], v[106:107], s[0:1], v[20:21]
	s_mov_b32 s0, 0xc2200000
	s_mov_b32 s1, 0xc2240000
	v_pk_add_f32 v[20:21], v[48:49], s[0:1] op_sel_hi:[0,1]
	v_cmp_le_f32_e32 vcc, 0, v21
	v_cmp_gt_f32_e64 s[8:9], s52, v21
	v_cmp_le_f32_e64 s[0:1], 0, v20
	v_cmp_gt_f32_e64 s[10:11], s52, v20
	s_and_b64 vcc, vcc, s[8:9]
	v_cndmask_b32_e32 v20, v160, v25, vcc
	s_and_b64 vcc, s[0:1], s[10:11]
	s_mov_b32 s0, 0x42080000
	s_mov_b32 s1, 0x420c0000
	v_cndmask_b32_e32 v21, v160, v24, vcc
	v_pk_fma_f32 v[24:25], v[106:107], s[0:1], v[18:19]
	s_mov_b32 s0, 0xc2080000
	s_mov_b32 s1, 0xc20c0000
	v_pk_add_f32 v[18:19], v[48:49], s[0:1] op_sel_hi:[0,1]
	v_cmp_le_f32_e32 vcc, 0, v19
	v_cmp_gt_f32_e64 s[8:9], s52, v19
	v_cmp_le_f32_e64 s[0:1], 0, v18
	v_cmp_gt_f32_e64 s[10:11], s52, v18
	s_and_b64 vcc, vcc, s[8:9]
	v_cndmask_b32_e32 v18, v160, v25, vcc
	s_and_b64 vcc, s[0:1], s[10:11]
	s_mov_b32 s0, 0xc2000000
	s_mov_b32 s1, 0xc2040000
	v_cndmask_b32_e32 v19, v160, v24, vcc
	v_pk_fma_f32 v[24:25], v[106:107], s[38:39], v[16:17]
	v_pk_add_f32 v[16:17], v[48:49], s[0:1] op_sel_hi:[0,1]
	v_cmp_le_f32_e32 vcc, 0, v17
	v_cmp_gt_f32_e64 s[8:9], s52, v17
	v_cmp_le_f32_e64 s[0:1], 0, v16
	v_cmp_gt_f32_e64 s[10:11], s52, v16
	s_and_b64 vcc, vcc, s[8:9]
	v_cndmask_b32_e32 v16, v160, v25, vcc
	s_and_b64 vcc, s[0:1], s[10:11]
	s_mov_b32 s0, 0x41d00000
	s_mov_b32 s1, 0x41d80000
	v_cndmask_b32_e32 v17, v160, v24, vcc
	v_pk_fma_f32 v[24:25], v[106:107], s[0:1], v[14:15]
	s_mov_b32 s0, 0xc1d00000
	s_mov_b32 s1, 0xc1d80000
	v_pk_add_f32 v[14:15], v[48:49], s[0:1] op_sel_hi:[0,1]
	v_cmp_le_f32_e32 vcc, 0, v15
	v_cmp_gt_f32_e64 s[8:9], s52, v15
	v_cmp_le_f32_e64 s[0:1], 0, v14
	v_cmp_gt_f32_e64 s[10:11], s52, v14
	s_and_b64 vcc, vcc, s[8:9]
	v_cndmask_b32_e32 v14, v160, v25, vcc
	s_and_b64 vcc, s[0:1], s[10:11]
	s_mov_b32 s0, 0x41c00000
	s_mov_b32 s1, 0x41c80000
	v_cndmask_b32_e32 v15, v160, v24, vcc
	v_pk_fma_f32 v[24:25], v[106:107], s[0:1], v[12:13]
	s_mov_b32 s0, 0xc1c00000
	s_mov_b32 s1, 0xc1c80000
	v_pk_add_f32 v[12:13], v[48:49], s[0:1] op_sel_hi:[0,1]
	v_cmp_le_f32_e32 vcc, 0, v13
	v_cmp_gt_f32_e64 s[8:9], s52, v13
	v_cmp_le_f32_e64 s[0:1], 0, v12
	v_cmp_gt_f32_e64 s[10:11], s52, v12
	s_and_b64 vcc, vcc, s[8:9]
	v_cndmask_b32_e32 v12, v160, v25, vcc
	s_and_b64 vcc, s[0:1], s[10:11]
	s_mov_b32 s0, 0x41900000
	s_mov_b32 s1, 0x41980000
	v_cndmask_b32_e32 v13, v160, v24, vcc
	v_pk_fma_f32 v[24:25], v[106:107], s[0:1], v[10:11]
	s_mov_b32 s0, 0xc1900000
	s_mov_b32 s1, 0xc1980000
	v_pk_add_f32 v[10:11], v[48:49], s[0:1] op_sel_hi:[0,1]
	v_cmp_le_f32_e32 vcc, 0, v11
	v_cmp_gt_f32_e64 s[8:9], s52, v11
	v_cmp_le_f32_e64 s[0:1], 0, v10
	v_cmp_gt_f32_e64 s[10:11], s52, v10
	s_and_b64 vcc, vcc, s[8:9]
	v_cndmask_b32_e32 v10, v160, v25, vcc
	s_and_b64 vcc, s[0:1], s[10:11]
	s_mov_b32 s0, 0xc1800000
	s_mov_b32 s1, 0xc1880000
	v_cndmask_b32_e32 v11, v160, v24, vcc
	v_pk_add_f32 v[24:25], v[48:49], s[0:1] op_sel_hi:[0,1]
	v_cmp_le_f32_e32 vcc, 0, v25
	v_cmp_gt_f32_e64 s[8:9], s52, v25
	v_cmp_le_f32_e64 s[0:1], 0, v24
	v_cmp_gt_f32_e64 s[10:11], s52, v24
	s_and_b64 vcc, vcc, s[8:9]
	v_cndmask_b32_e32 v24, v160, v9, vcc
	s_and_b64 vcc, s[0:1], s[10:11]
	s_mov_b32 s0, 0xc1200000
	s_mov_b32 s1, 0xc1300000
	v_cndmask_b32_e32 v25, v160, v8, vcc
	v_pk_add_f32 v[8:9], v[48:49], s[0:1] op_sel_hi:[0,1]
	v_cmp_le_f32_e32 vcc, 0, v9
	v_cmp_gt_f32_e64 s[8:9], s52, v9
	v_cmp_le_f32_e64 s[0:1], 0, v8
	v_cmp_gt_f32_e64 s[10:11], s52, v8
	s_and_b64 vcc, vcc, s[8:9]
	v_cndmask_b32_e32 v26, v160, v7, vcc
	s_and_b64 vcc, s[0:1], s[10:11]
	s_mov_b32 s0, 0xc1000000
	s_mov_b32 s1, 0xc1100000
	v_cndmask_b32_e32 v27, v160, v6, vcc
	v_pk_fma_f32 v[6:7], v[106:107], s[70:71], v[4:5]
	v_pk_add_f32 v[4:5], v[48:49], s[0:1] op_sel_hi:[0,1]
	v_cmp_le_f32_e32 vcc, 0, v5
	v_cmp_gt_f32_e64 s[8:9], s52, v5
	v_cmp_le_f32_e64 s[0:1], 0, v4
	v_cmp_gt_f32_e64 s[10:11], s52, v4
	s_and_b64 vcc, vcc, s[8:9]
	v_cndmask_b32_e32 v4, v160, v7, vcc
	s_and_b64 vcc, s[0:1], s[10:11]
	s_mov_b32 s0, -2.0
	s_mov_b32 s1, 0xc0400000
	v_cndmask_b32_e32 v5, v160, v6, vcc
	v_pk_fma_f32 v[6:7], v[106:107], s[68:69], v[2:3]
	v_pk_add_f32 v[2:3], v[48:49], s[0:1] op_sel_hi:[0,1]
	v_cmp_le_f32_e32 vcc, 0, v3
	v_cmp_gt_f32_e64 s[8:9], s52, v3
	v_cmp_le_f32_e64 s[0:1], 0, v2
	v_cmp_gt_f32_e64 s[10:11], s52, v2
	s_and_b64 vcc, vcc, s[8:9]
	v_cndmask_b32_e32 v2, v160, v7, vcc
	s_and_b64 vcc, s[0:1], s[10:11]
	v_cndmask_b32_e32 v3, v160, v6, vcc
	v_max3_f32 v6, v57, v3, v2
	v_max3_f32 v6, v6, v5, v4
	v_max3_f32 v6, v6, v27, v26
	v_max3_f32 v6, v6, v25, v24
	v_max3_f32 v6, v6, v11, v10
	v_max3_f32 v6, v6, v13, v12
	v_max3_f32 v6, v6, v15, v14
	v_max3_f32 v6, v6, v17, v16
	v_max3_f32 v6, v6, v19, v18
	v_max3_f32 v6, v6, v21, v20
	v_max3_f32 v6, v6, v23, v22
	v_max3_f32 v6, v6, v1, v0
	v_max3_f32 v6, v6, v54, v53
	v_max3_f32 v6, v6, v51, v52
	v_max3_f32 v6, v6, v49, v50
	v_fma_f32 v7, -v106, v48, v6
	v_cmp_lt_f32_e32 vcc, s76, v6
	s_nop 1
	v_cndmask_b32_e32 v28, v160, v7, vcc
	v_mov_b32_e32 v29, v28
	s_nop 1
	v_permlane32_swap_b32_e32 v29, v28
	s_nop 1
	v_cmp_lt_f32_e32 vcc, s76, v55
	ds_read_b128 v[6:9], v144 offset:9216
	s_waitcnt lgkmcnt(1)
; DI float fexp2(float x) { return __builtin_amdgcn_exp2f(x); }
; template <int KSTRIDE, bool WIN, int MASK, int MODE>
; DI void attend_tile(const u16* Ks, const u16* Vts, const bf16x8 (&qf)[4], f32x16 (&O)[2], float& m, float& l, int dbase,
;                     float slope2, bool lanesel, float invl, unsigned* imp_row, int mbase, int lr, int hh) {
;     ...
;   float rs = 0.f;
; #pragma unroll
;   for (int kt = 0; kt < 2; ++kt)
; #pragma unroll
;     for (int e = 0; e < 16; ++e) {
;       float v = s[kt][e];
;       float pv;
;       if (MASK == 1) pv = (v > -1e29f) ? fexp2(v - shift) : 0.f;
;       else pv = fexp2(v - shift);
;       if (MODE == 2) pv *= invl;
;       s[kt][e] = pv;
;       rs += pv;
;     }
;   if (MODE != 2) l = l * alpha + rs;
;   if (MODE == 1) return;
;   if (MODE == 0) {
; #pragma unroll
;     for (int e = 0; e < 16; ++e) { O[0][e] *= alpha; O[1][e] *= alpha; }
	v_max3_f32 v145, v143, v28, v29
	v_fma_f32 v48, v106, v48, v145
	v_sub_f32_e32 v29, v55, v48
	v_exp_f32_e32 v29, v29
	v_sub_f32_e32 v30, v56, v48
	v_exp_f32_e32 v30, v30
	v_sub_f32_e32 v31, v3, v48
	v_cndmask_b32_e32 v55, 0, v29, vcc
	v_cmp_lt_f32_e32 vcc, s76, v56
	v_exp_f32_e32 v31, v31
	v_add_f32_e32 v29, 0, v55
	v_cndmask_b32_e32 v56, 0, v30, vcc
	v_sub_f32_e32 v30, v2, v48
	v_exp_f32_e32 v30, v30
	v_cmp_lt_f32_e32 vcc, s76, v2
	v_add_f32_e32 v29, v56, v29
	v_sub_f32_e32 v28, v143, v145
	v_cndmask_b32_e32 v57, 0, v30, vcc
	v_cmp_lt_f32_e32 vcc, s76, v3
	v_sub_f32_e32 v3, v4, v48
	v_exp_f32_e32 v3, v3
	v_cndmask_b32_e32 v58, 0, v31, vcc
	v_add_f32_e32 v2, v58, v29
	v_sub_f32_e32 v29, v5, v48
	v_cmp_lt_f32_e32 vcc, s76, v4
	v_exp_f32_e32 v29, v29
	v_sub_f32_e32 v4, v27, v48
	v_cndmask_b32_e32 v59, 0, v3, vcc
	v_sub_f32_e32 v3, v26, v48
	v_exp_f32_e32 v3, v3
	v_exp_f32_e32 v4, v4
	v_cmp_lt_f32_e32 vcc, s76, v5
	v_add_f32_e32 v2, v57, v2
	v_exp_f32_e32 v148, v28
	v_cndmask_b32_e32 v60, 0, v29, vcc
	v_cmp_lt_f32_e32 vcc, s76, v26
	v_add_f32_e32 v2, v60, v2
	v_add_f32_e32 v2, v59, v2
	v_cndmask_b32_e32 v61, 0, v3, vcc
	v_cmp_lt_f32_e32 vcc, s76, v27
	v_sub_f32_e32 v3, v24, v48
	v_exp_f32_e32 v3, v3
	v_cndmask_b32_e32 v62, 0, v4, vcc
	v_sub_f32_e32 v4, v25, v48
	v_exp_f32_e32 v4, v4
	v_cmp_lt_f32_e32 vcc, s76, v24
	v_add_f32_e32 v2, v62, v2
	v_add_f32_e32 v2, v61, v2
	v_cndmask_b32_e32 v143, 0, v3, vcc
	v_cmp_lt_f32_e32 vcc, s76, v25
	v_sub_f32_e32 v3, v10, v48
	v_exp_f32_e32 v3, v3
	v_cndmask_b32_e32 v146, 0, v4, vcc
	v_sub_f32_e32 v4, v11, v48
	v_exp_f32_e32 v4, v4
	v_cmp_lt_f32_e32 vcc, s76, v10
	v_add_f32_e32 v2, v146, v2
	v_add_f32_e32 v2, v143, v2
	v_cndmask_b32_e32 v147, 0, v3, vcc
	v_cmp_lt_f32_e32 vcc, s76, v11
	v_sub_f32_e32 v3, v12, v48
	v_exp_f32_e32 v3, v3
	v_cndmask_b32_e32 v149, 0, v4, vcc
	v_sub_f32_e32 v4, v13, v48
	v_exp_f32_e32 v4, v4
	v_cmp_lt_f32_e32 vcc, s76, v12
	v_add_f32_e32 v2, v149, v2
	v_add_f32_e32 v2, v147, v2
	v_cndmask_b32_e32 v150, 0, v3, vcc
	v_cmp_lt_f32_e32 vcc, s76, v13
	v_sub_f32_e32 v3, v14, v48
	v_exp_f32_e32 v3, v3
	v_cndmask_b32_e32 v151, 0, v4, vcc
	v_sub_f32_e32 v4, v15, v48
	v_exp_f32_e32 v4, v4
	v_cmp_lt_f32_e32 vcc, s76, v14
	v_add_f32_e32 v2, v151, v2
	v_add_f32_e32 v2, v150, v2
	v_cndmask_b32_e32 v152, 0, v3, vcc
	v_cmp_lt_f32_e32 vcc, s76, v15
	v_sub_f32_e32 v3, v16, v48
	v_exp_f32_e32 v3, v3
	v_cndmask_b32_e32 v153, 0, v4, vcc
	v_sub_f32_e32 v4, v17, v48
	v_exp_f32_e32 v4, v4
	v_cmp_lt_f32_e32 vcc, s76, v16
	v_add_f32_e32 v2, v153, v2
	v_add_f32_e32 v2, v152, v2
	v_cndmask_b32_e32 v164, 0, v3, vcc
	v_cmp_lt_f32_e32 vcc, s76, v17
	v_sub_f32_e32 v3, v18, v48
	v_exp_f32_e32 v3, v3
	v_cndmask_b32_e32 v165, 0, v4, vcc
	v_sub_f32_e32 v4, v19, v48
	v_exp_f32_e32 v4, v4
	v_cmp_lt_f32_e32 vcc, s76, v18
	v_add_f32_e32 v2, v165, v2
	v_add_f32_e32 v2, v164, v2
	v_cndmask_b32_e32 v166, 0, v3, vcc
	v_cmp_lt_f32_e32 vcc, s76, v19
	v_sub_f32_e32 v3, v20, v48
	v_exp_f32_e32 v3, v3
	v_cndmask_b32_e32 v167, 0, v4, vcc
	v_sub_f32_e32 v4, v21, v48
	v_exp_f32_e32 v4, v4
	v_cmp_lt_f32_e32 vcc, s76, v20
	v_add_f32_e32 v2, v167, v2
	v_cvt_pk_bf16_f32 v57, v58, v57
	v_cndmask_b32_e32 v168, 0, v3, vcc
	v_cmp_lt_f32_e32 vcc, s76, v21
	v_sub_f32_e32 v3, v22, v48
	v_exp_f32_e32 v3, v3
	v_cndmask_b32_e32 v169, 0, v4, vcc
	v_sub_f32_e32 v4, v23, v48
	v_exp_f32_e32 v4, v4
	v_cmp_lt_f32_e32 vcc, s76, v22
	v_cvt_pk_bf16_f32 v58, v60, v59
	v_cvt_pk_bf16_f32 v59, v62, v61
	v_cndmask_b32_e32 v170, 0, v3, vcc
	v_cmp_lt_f32_e32 vcc, s76, v23
	v_sub_f32_e32 v3, v0, v48
	v_exp_f32_e32 v3, v3
	v_cndmask_b32_e32 v171, 0, v4, vcc
	v_sub_f32_e32 v4, v1, v48
	ds_read_b128 v[60:63], v144 offset:13824
	v_add_f32_e32 v2, v166, v2
	v_exp_f32_e32 v4, v4
	v_pk_mul_f32 v[16:17], v[108:109], v[148:149] op_sel_hi:[1,0]
	v_pk_mul_f32 v[18:19], v[110:111], v[148:149] op_sel_hi:[1,0]
	v_pk_mul_f32 v[20:21], v[112:113], v[148:149] op_sel_hi:[1,0]
	v_pk_mul_f32 v[22:23], v[114:115], v[148:149] op_sel_hi:[1,0]
	v_pk_mul_f32 v[24:25], v[118:119], v[148:149] op_sel_hi:[1,0]
	v_pk_mul_f32 v[26:27], v[120:121], v[148:149] op_sel_hi:[1,0]
	v_pk_mul_f32 v[28:29], v[122:123], v[148:149] op_sel_hi:[1,0]
	v_pk_mul_f32 v[30:31], v[124:125], v[148:149] op_sel_hi:[1,0]
	v_cvt_pk_bf16_f32 v56, v55, v56
	v_add_f32_e32 v2, v169, v2
	v_add_f32_e32 v2, v168, v2
	s_waitcnt lgkmcnt(1)
; #define MFMA32(a, b, c) __builtin_amdgcn_mfma_f32_32x32x16_bf16((a), (b), (c), 0, 0, 0)
; template <int KSTRIDE, bool WIN, int MASK, int MODE>
; DI void attend_tile(const u16* Ks, const u16* Vts, const bf16x8 (&qf)[4], f32x16 (&O)[2], float& m, float& l, int dbase,
;                     float slope2, bool lanesel, float invl, unsigned* imp_row, int mbase, int lr, int hh) {
;     ...
;   if (MODE != 2) l = l * alpha + rs;
;   if (MODE == 1) return;
;   if (MODE == 0) {
; #pragma unroll
;     for (int e = 0; e < 16; ++e) { O[0][e] *= alpha; O[1][e] *= alpha; }
;   }
;   if (MODE == 2) {
; #pragma unroll
;     for (int kt = 0; kt < 2; ++kt)
; #pragma unroll
;       for (int q4 = 0; q4 < 4; ++q4) {
;         float qsum = s[kt][q4 * 4] + s[kt][q4 * 4 + 1] + s[kt][q4 * 4 + 2] + s[kt][q4 * 4 + 3];
;         float last = s[kt][q4 * 4 + 3];
;         int mi = mbase + kt * 8 + 2 * q4 + hh;
;         atomicAdd(imp_row + mi, (unsigned)(qsum * 1048576.f + 0.5f));
;         if (mi + 1 < 64) atomicAdd(imp_row + mi + 1, (unsigned)(last * 1048576.f + 0.5f));
;       }
;   }
; #pragma unroll
;   for (int kt = 0; kt < 2; ++kt)
; #pragma unroll
;     for (int sx = 0; sx < 2; ++sx) {
;       unsigned pk[4];
; #pragma unroll
;       for (int q = 0; q < 4; ++q) pk[q] = pack2(s[kt][8 * sx + 2 * q], s[kt][8 * sx + 2 * q + 1]);
;       bf16x8 pb;
;       {
;         u32x4 t4 = {pk[0], pk[1], pk[2], pk[3]};
;         pb = __builtin_bit_cast(bf16x8, t4);
;       }
; #pragma unroll
;       for (int dt = 0; dt < 2; ++dt) {
;         bf16x8 a = *(const bf16x8*)(Vts + (dt * 32 + lr) * 72 + kt * 32 + 16 * sx + 8 * hh);
;         O[dt] = MFMA32(a, pb, O[dt]);
;       }
;     }
	v_mfma_f32_32x32x16_bf16 v[16:31], v[6:9], v[56:59], v[16:31]
	v_cmp_lt_f32_e32 vcc, s76, v0
	v_add_f32_e32 v2, v171, v2
	v_add_f32_e32 v2, v170, v2
	v_cndmask_b32_e32 v172, 0, v3, vcc
	v_cmp_lt_f32_e32 vcc, s76, v1
	ds_read_b128 v[80:83], v144 offset:9248
	ds_read_b128 v[84:87], v144 offset:9312
	v_cndmask_b32_e32 v173, 0, v4, vcc
	v_add_f32_e32 v0, v173, v2
	v_add_f32_e32 v174, v172, v0
	v_sub_f32_e32 v0, v54, v48
	v_exp_f32_e32 v175, v0
	v_pk_mul_f32 v[0:1], v[132:133], v[148:149] op_sel_hi:[1,0]
	v_pk_mul_f32 v[2:3], v[134:135], v[148:149] op_sel_hi:[1,0]
	v_pk_mul_f32 v[4:5], v[138:139], v[148:149] op_sel_hi:[1,0]
	v_pk_mul_f32 v[6:7], v[126:127], v[148:149] op_sel_hi:[1,0]
	v_pk_mul_f32 v[8:9], v[128:129], v[148:149] op_sel_hi:[1,0]
	v_pk_mul_f32 v[10:11], v[130:131], v[148:149] op_sel_hi:[1,0]
	v_pk_mul_f32 v[12:13], v[136:137], v[148:149] op_sel_hi:[1,0]
	v_pk_mul_f32 v[14:15], v[140:141], v[148:149] op_sel_hi:[1,0]
	v_sub_f32_e32 v55, v53, v48
	v_exp_f32_e32 v55, v55
	s_waitcnt lgkmcnt(2)
	v_mfma_f32_32x32x16_bf16 v[0:15], v[60:63], v[56:59], v[0:15]
	v_cvt_pk_bf16_f32 v56, v146, v143
	v_cvt_pk_bf16_f32 v57, v149, v147
	v_cvt_pk_bf16_f32 v58, v151, v150
	v_cvt_pk_bf16_f32 v59, v153, v152
	ds_read_b128 v[60:63], v144 offset:9280
	ds_read_b128 v[108:111], v144 offset:13888
	v_cmp_lt_f32_e32 vcc, s76, v53
	s_waitcnt lgkmcnt(3)
	v_mfma_f32_32x32x16_bf16 v[16:31], v[80:83], v[56:59], v[16:31]
	ds_read_b128 v[80:83], v144 offset:13856
	v_cndmask_b32_e32 v112, 0, v55, vcc
	v_cmp_lt_f32_e32 vcc, s76, v54
	v_sub_f32_e32 v54, v52, v48
	v_exp_f32_e32 v54, v54
	v_cndmask_b32_e32 v113, 0, v175, vcc
	v_sub_f32_e32 v53, v51, v48
	s_waitcnt lgkmcnt(0)
	v_mfma_f32_32x32x16_bf16 v[0:15], v[80:83], v[56:59], v[0:15]
	v_cmp_lt_f32_e32 vcc, s76, v52
	v_exp_f32_e32 v56, v53
	v_cvt_pk_bf16_f32 v52, v165, v164
	v_cndmask_b32_e32 v57, 0, v54, vcc
	v_cvt_pk_bf16_f32 v53, v167, v166
	v_cvt_pk_bf16_f32 v54, v169, v168
	v_cvt_pk_bf16_f32 v55, v171, v170
	v_cmp_lt_f32_e32 vcc, s76, v51
	v_sub_f32_e32 v51, v50, v48
	v_mfma_f32_32x32x16_bf16 v[16:31], v[60:63], v[52:55], v[16:31]
	v_exp_f32_e32 v51, v51
	v_sub_f32_e32 v48, v49, v48
	v_exp_f32_e32 v48, v48
	v_cndmask_b32_e32 v56, 0, v56, vcc
	v_cmp_lt_f32_e32 vcc, s76, v50
	v_cvt_pk_bf16_f32 v50, v56, v57
	v_add_f32_e32 v60, v113, v174
	v_mfma_f32_32x32x16_bf16 v[0:15], v[108:111], v[52:55], v[0:15]
	ds_read_b128 v[52:55], v144 offset:13920
	v_cndmask_b32_e32 v58, 0, v51, vcc
	v_cmp_lt_f32_e32 vcc, s76, v49
	v_cvt_pk_bf16_f32 v49, v113, v112
	v_add_f32_e32 v60, v112, v60
	v_cndmask_b32_e32 v59, 0, v48, vcc
	v_cvt_pk_bf16_f32 v48, v173, v172
	v_cvt_pk_bf16_f32 v51, v59, v58
	v_add_f32_e32 v56, v56, v60
	v_add_f32_e32 v56, v57, v56
	v_mfma_f32_32x32x16_bf16 v[16:31], v[84:87], v[48:51], v[16:31]
	v_add_f32_e32 v56, v59, v56
	v_add_f32_e32 v146, v58, v56
	v_fmac_f32_e32 v146, v142, v148
	s_waitcnt lgkmcnt(0)
	v_mfma_f32_32x32x16_bf16 v[0:15], v[52:55], v[48:51], v[0:15]

; #define MFMA32(a, b, c) __builtin_amdgcn_mfma_f32_32x32x16_bf16((a), (b), (c), 0, 0, 0)
; template <int KSTRIDE, bool WIN, int MASK, int MODE>
; DI void attend_tile(const u16* Ks, const u16* Vts, const bf16x8 (&qf)[4], f32x16 (&O)[2], float& m, float& l, int dbase,
;                     float slope2, bool lanesel, float invl, unsigned* imp_row, int mbase, int lr, int hh) {
;   f32x16 s[2];
; #pragma unroll
;   for (int kt = 0; kt < 2; ++kt) {
; #pragma unroll
;     for (int e = 0; e < 16; ++e) s[kt][e] = 0.f;
; #pragma unroll
;     for (int ks = 0; ks < 4; ++ks) {
;       bf16x8 a = *(const bf16x8*)(Ks + (kt * 32 + lr) * 72 + ks * 16 + hh * 8);
;       s[kt] = MFMA32(a, qf[ks], s[kt]);
;     }
;   }
;   const float fd0 = (float)(dbase - KSTRIDE * 4 * hh);
;   const float ct = slope2 * fd0;
;   float mx = -1e30f;
; #pragma unroll
;   for (int kt = 0; kt < 2; ++kt)
; #pragma unroll
;     for (int e = 0; e < 16; ++e) {
;       const float Ke = (float)(KSTRIDE * (kt * 32 + (e & 3) + 8 * (e >> 2)));
;       float v = fmaf(slope2, Ke, s[kt][e]);
;       if (MASK == 1) {
;         const float fd = fd0 - Ke;
;         bool valid = fd >= 0.f;
;         if (WIN) valid = valid && (fd < 512.f);
;         valid = valid && lanesel;
;         v = valid ? v : -1e30f;
;       }
;       s[kt][e] = v;
;       mx = fmaxf(mx, v);
;     }
;   mx = (mx > -1e29f) ? mx - ct : -1e30f;
;   mx = fmaxf(mx, __shfl_xor(mx, 32));
;   if (MASK == 2) mx = lanesel ? mx : -1e30f;
; DI void attn_item(const Params& p, int item, char* smem) {
;     ...
;       bool ls = (j < 32) ? ((mylo >> j) & 1u) : ((myhi >> (j - 32)) & 1u);
;       if (j < qb) attend_tile<1, false, 2, 0>(Ks, Vts, qf, O, m, l, t - 64 * j, slope2, ls, 0.f, nullptr, 0, lr, hh);
;       else attend_tile<1, false, 1, 0>(Ks, Vts, qf, O, m, l, t - 64 * j, slope2, ls, 0.f, nullptr, 0, lr, hh);
.LBB0_642:
	v_add3_u32 v165, s81, v161, v162
	s_waitcnt lgkmcnt(8)
	ds_read_b128 v[48:51], v165
	s_waitcnt lgkmcnt(8)
	ds_read_b128 v[44:47], v165 offset:32
	s_waitcnt lgkmcnt(8)
	ds_read_b128 v[32:35], v165 offset:64
	s_waitcnt lgkmcnt(8)
	ds_read_b128 v[36:39], v165 offset:96
	s_waitcnt lgkmcnt(8)
	ds_read_b128 v[40:43], v165 offset:4608
	v_sub_co_u32_e64 v1, vcc, s80, 32
	v_lshrrev_b32_e32 v0, s80, v62
	v_lshrrev_b32_e32 v1, v1, v63
	v_cndmask_b32_e32 v0, v1, v0, vcc
	v_and_b32_e32 v0, 1, v0
	v_cmp_eq_u32_e64 s[0:1], 1, v0
	s_cmp_ge_u32 s80, s86
	s_mov_b64 vcc, -1
	s_cbranch_scc0 .LBB0_644
	s_waitcnt lgkmcnt(4)
	v_mfma_f32_32x32x16_bf16 v[16:31], v[48:51], v[64:67], 0
	ds_read_b128 v[52:55], v165 offset:4640
	ds_read_b128 v[170:173], v165 offset:4672
	s_lshl_b32 s81, s80, 6
	s_waitcnt lgkmcnt(2)
	v_mfma_f32_32x32x16_bf16 v[0:15], v[40:43], v[64:67], 0
	v_mfma_f32_32x32x16_bf16 v[16:31], v[44:47], v[68:71], v[16:31]
	s_waitcnt lgkmcnt(1)
	v_mfma_f32_32x32x16_bf16 v[0:15], v[52:55], v[68:71], v[0:15]
	ds_read_b128 v[52:55], v165 offset:4704
	v_mfma_f32_32x32x16_bf16 v[16:31], v[32:35], v[72:75], v[16:31]
	s_waitcnt lgkmcnt(1)
	v_mfma_f32_32x32x16_bf16 v[0:15], v[170:173], v[72:75], v[0:15]
	v_mfma_f32_32x32x16_bf16 v[16:31], v[36:39], v[76:79], v[16:31]
	s_waitcnt lgkmcnt(0)
	v_mfma_f32_32x32x16_bf16 v[0:15], v[52:55], v[76:79], v[0:15]
	v_subrev_u32_e32 v52, s81, v57
	v_cmp_lt_i32_e32 vcc, -1, v52
	s_nop 7
	v_fma_f32 v16, 0, v106, v16
	s_and_b64 vcc, vcc, s[0:1]
	v_cndmask_b32_e32 v16, v160, v16, vcc
	v_cmp_lt_i32_e32 vcc, 0, v52
	v_add_f32_e32 v17, v106, v17
	s_and_b64 vcc, vcc, s[0:1]
	v_cndmask_b32_e32 v17, v160, v17, vcc
	v_cmp_lt_i32_e32 vcc, 1, v52
	v_fma_f32 v18, 2.0, v106, v18
	s_and_b64 vcc, vcc, s[0:1]
	v_cndmask_b32_e32 v18, v160, v18, vcc
	v_cmp_lt_i32_e32 vcc, 2, v52
	v_fmamk_f32 v19, v106, 0x40400000, v19
	s_and_b64 vcc, vcc, s[0:1]
	v_cndmask_b32_e32 v19, v160, v19, vcc
	v_cmp_lt_i32_e32 vcc, 7, v52
	v_fmamk_f32 v20, v106, 0x41000000, v20
	s_and_b64 vcc, vcc, s[0:1]
	v_cndmask_b32_e32 v20, v160, v20, vcc
	v_cmp_lt_i32_e32 vcc, 8, v52
	v_fmamk_f32 v21, v106, 0x41100000, v21
	s_and_b64 vcc, vcc, s[0:1]
	v_cndmask_b32_e32 v21, v160, v21, vcc
	v_cmp_lt_i32_e32 vcc, 9, v52
	v_fmamk_f32 v22, v106, 0x41200000, v22
	s_and_b64 vcc, vcc, s[0:1]
	v_cndmask_b32_e32 v22, v160, v22, vcc
	v_cmp_lt_i32_e32 vcc, 10, v52
	v_fmamk_f32 v23, v106, 0x41300000, v23
	s_and_b64 vcc, vcc, s[0:1]
	v_cndmask_b32_e32 v23, v160, v23, vcc
	v_cmp_lt_i32_e32 vcc, 15, v52
	v_fmamk_f32 v24, v106, 0x41800000, v24
	s_and_b64 vcc, vcc, s[0:1]
	v_cndmask_b32_e32 v24, v160, v24, vcc
	v_cmp_lt_i32_e32 vcc, 16, v52
	v_fmamk_f32 v25, v106, 0x41880000, v25
	s_and_b64 vcc, vcc, s[0:1]
	v_cndmask_b32_e32 v25, v160, v25, vcc
	v_cmp_lt_i32_e32 vcc, 17, v52
	v_fmamk_f32 v26, v106, 0x41900000, v26
	s_and_b64 vcc, vcc, s[0:1]
	v_cndmask_b32_e32 v26, v160, v26, vcc
	v_cmp_lt_i32_e32 vcc, 18, v52
	v_fmamk_f32 v27, v106, 0x41980000, v27
	s_and_b64 vcc, vcc, s[0:1]
	v_cndmask_b32_e32 v27, v160, v27, vcc
	v_cmp_lt_i32_e32 vcc, 23, v52
	v_fmamk_f32 v28, v106, 0x41c00000, v28
	s_and_b64 vcc, vcc, s[0:1]
	v_cndmask_b32_e32 v28, v160, v28, vcc
	v_cmp_lt_i32_e32 vcc, 24, v52
	v_fmamk_f32 v29, v106, 0x41c80000, v29
	s_and_b64 vcc, vcc, s[0:1]
	v_cndmask_b32_e32 v29, v160, v29, vcc
	v_cmp_lt_i32_e32 vcc, 25, v52
	v_fmamk_f32 v30, v106, 0x41d00000, v30
	s_and_b64 vcc, vcc, s[0:1]
	v_cndmask_b32_e32 v30, v160, v30, vcc
	v_cmp_lt_i32_e32 vcc, 26, v52
	v_fmac_f32_e32 v31, 0x41d80000, v106
	s_and_b64 vcc, vcc, s[0:1]
	v_cndmask_b32_e32 v31, v160, v31, vcc
	v_cmp_lt_i32_e32 vcc, 31, v52
	v_fmamk_f32 v0, v106, 0x42000000, v0
	s_and_b64 vcc, vcc, s[0:1]
	v_cndmask_b32_e32 v0, v160, v0, vcc
	v_cmp_lt_i32_e32 vcc, 32, v52
	v_fmamk_f32 v1, v106, 0x42040000, v1
	s_and_b64 vcc, vcc, s[0:1]
	v_cndmask_b32_e32 v1, v160, v1, vcc
	v_cmp_lt_i32_e32 vcc, 33, v52
	v_fmamk_f32 v2, v106, 0x42080000, v2
	s_and_b64 vcc, vcc, s[0:1]
	v_cndmask_b32_e32 v2, v160, v2, vcc
	v_cmp_lt_i32_e32 vcc, 34, v52
	v_fmamk_f32 v3, v106, 0x420c0000, v3
	s_and_b64 vcc, vcc, s[0:1]
	v_cndmask_b32_e32 v3, v160, v3, vcc
	v_cmp_lt_i32_e32 vcc, 39, v52
	v_fmamk_f32 v4, v106, 0x42200000, v4
	s_and_b64 vcc, vcc, s[0:1]
	v_cndmask_b32_e32 v4, v160, v4, vcc
	v_cmp_lt_i32_e32 vcc, 40, v52
	v_fmamk_f32 v5, v106, 0x42240000, v5
	s_and_b64 vcc, vcc, s[0:1]
	v_cndmask_b32_e32 v5, v160, v5, vcc
	v_cmp_lt_i32_e32 vcc, 41, v52
	v_fmamk_f32 v6, v106, 0x42280000, v6
	s_and_b64 vcc, vcc, s[0:1]
	v_cndmask_b32_e32 v6, v160, v6, vcc
	v_cmp_lt_i32_e32 vcc, 42, v52
	v_fmamk_f32 v7, v106, 0x422c0000, v7
	s_and_b64 vcc, vcc, s[0:1]
	v_cndmask_b32_e32 v7, v160, v7, vcc
	v_cmp_lt_i32_e32 vcc, 47, v52
	v_fmamk_f32 v8, v106, 0x42400000, v8
	s_and_b64 vcc, vcc, s[0:1]
	v_max3_f32 v54, v16, s95, v17
	v_cndmask_b32_e32 v8, v160, v8, vcc
	v_cmp_lt_i32_e32 vcc, 48, v52
	v_max3_f32 v54, v54, v18, v19
	v_fmamk_f32 v9, v106, 0x42440000, v9
	s_and_b64 vcc, vcc, s[0:1]
	v_max3_f32 v54, v54, v20, v21
	v_cndmask_b32_e32 v9, v160, v9, vcc
	v_cmp_lt_i32_e32 vcc, 49, v52
	v_max3_f32 v54, v54, v22, v23
	v_fmamk_f32 v10, v106, 0x42480000, v10
	s_and_b64 vcc, vcc, s[0:1]
	v_max3_f32 v54, v54, v24, v25
	v_cndmask_b32_e32 v10, v160, v10, vcc
	v_cmp_lt_i32_e32 vcc, 50, v52
	v_max3_f32 v54, v54, v26, v27
	v_fmamk_f32 v11, v106, 0x424c0000, v11
	s_and_b64 vcc, vcc, s[0:1]
	v_max3_f32 v54, v54, v28, v29
	v_cndmask_b32_e32 v11, v160, v11, vcc
	v_cmp_lt_i32_e32 vcc, 55, v52
	v_max3_f32 v54, v54, v30, v31
	v_fmamk_f32 v12, v106, 0x42600000, v12
	s_and_b64 vcc, vcc, s[0:1]
	v_max3_f32 v54, v54, v0, v1
	v_cndmask_b32_e32 v12, v160, v12, vcc
	v_cmp_lt_i32_e32 vcc, 56, v52
	v_max3_f32 v54, v54, v2, v3
	v_fmamk_f32 v13, v106, 0x42640000, v13
	s_and_b64 vcc, vcc, s[0:1]
	v_max3_f32 v54, v54, v4, v5
	v_cndmask_b32_e32 v13, v160, v13, vcc
	v_cmp_lt_i32_e32 vcc, 57, v52
	v_max3_f32 v54, v54, v6, v7
	v_fmamk_f32 v14, v106, 0x42680000, v14
	s_and_b64 vcc, vcc, s[0:1]
	v_cvt_f32_i32_e32 v53, v52
	v_max3_f32 v54, v54, v8, v9
	v_cndmask_b32_e32 v14, v160, v14, vcc
	v_cmp_lt_i32_e32 vcc, 58, v52
	v_max3_f32 v54, v54, v10, v11
	v_fmac_f32_e32 v15, 0x426c0000, v106
	s_and_b64 vcc, vcc, s[0:1]
	v_max3_f32 v54, v54, v12, v13
	v_cndmask_b32_e32 v15, v160, v15, vcc
	v_max3_f32 v52, v54, v14, v15
	v_cmp_lt_f32_e32 vcc, s76, v52
	v_fma_f32 v52, -v106, v53, v52
	s_nop 0
	v_cndmask_b32_e32 v52, v160, v52, vcc
	v_mov_b32_e32 v54, v52
	s_nop 1
	v_permlane32_swap_b32_e32 v54, v52
	s_nop 1
	v_cmp_lt_f32_e32 vcc, s76, v16
	s_waitcnt lgkmcnt(0)
; DI float fexp2(float x) { return __builtin_amdgcn_exp2f(x); }
; template <int KSTRIDE, bool WIN, int MASK, int MODE>
; DI void attend_tile(const u16* Ks, const u16* Vts, const bf16x8 (&qf)[4], f32x16 (&O)[2], float& m, float& l, int dbase,
;                     float slope2, bool lanesel, float invl, unsigned* imp_row, int mbase, int lr, int hh) {
;     ...
;   float rs = 0.f;
; #pragma unroll
;   for (int kt = 0; kt < 2; ++kt)
; #pragma unroll
;     for (int e = 0; e < 16; ++e) {
;       float v = s[kt][e];
;       float pv;
;       if (MASK == 1) pv = (v > -1e29f) ? fexp2(v - shift) : 0.f;
;       else pv = fexp2(v - shift);
;       if (MODE == 2) pv *= invl;
;       s[kt][e] = pv;
;       rs += pv;
;     }
;   if (MODE != 2) l = l * alpha + rs;
;   if (MODE == 1) return;
;   if (MODE == 0) {
; #pragma unroll
;     for (int e = 0; e < 16; ++e) { O[0][e] *= alpha; O[1][e] *= alpha; }
	v_max3_f32 v166, v169, v52, v54
	v_fma_f32 v53, v106, v53, v166
	v_sub_f32_e32 v16, v16, v53
	v_exp_f32_e32 v16, v16
	v_sub_f32_e32 v52, v169, v166
	v_cndmask_b32_e32 v54, 0, v16, vcc
	v_cmp_lt_f32_e32 vcc, s76, v17
	v_sub_f32_e32 v17, v17, v53
	v_exp_f32_e32 v17, v17
	v_add_f32_e32 v16, 0, v54
	v_cndmask_b32_e32 v55, 0, v17, vcc
	v_sub_f32_e32 v17, v18, v53
	v_exp_f32_e32 v17, v17
	v_cmp_lt_f32_e32 vcc, s76, v18
	v_add_f32_e32 v16, v55, v16
	s_nop 0
	v_cndmask_b32_e32 v194, 0, v17, vcc
	v_sub_f32_e32 v17, v19, v53
	v_exp_f32_e32 v17, v17
	v_cmp_lt_f32_e32 vcc, s76, v19
	v_add_f32_e32 v16, v194, v16
	s_nop 0
	v_cndmask_b32_e32 v195, 0, v17, vcc
	v_sub_f32_e32 v17, v20, v53
	v_exp_f32_e32 v17, v17
	v_cmp_lt_f32_e32 vcc, s76, v20
	v_add_f32_e32 v16, v195, v16
	s_nop 0
	v_cndmask_b32_e32 v196, 0, v17, vcc
	v_sub_f32_e32 v17, v21, v53
	v_exp_f32_e32 v17, v17
	v_cmp_lt_f32_e32 vcc, s76, v21
	v_add_f32_e32 v16, v196, v16
	s_nop 0
	v_cndmask_b32_e32 v197, 0, v17, vcc
	v_sub_f32_e32 v17, v22, v53
	v_exp_f32_e32 v17, v17
	v_cmp_lt_f32_e32 vcc, s76, v22
	v_add_f32_e32 v16, v197, v16
	s_nop 0
	v_cndmask_b32_e32 v198, 0, v17, vcc
	v_sub_f32_e32 v17, v23, v53
	v_exp_f32_e32 v17, v17
	v_cmp_lt_f32_e32 vcc, s76, v23
	v_add_f32_e32 v16, v198, v16
	s_nop 0
	v_cndmask_b32_e32 v199, 0, v17, vcc
	v_sub_f32_e32 v17, v24, v53
	v_exp_f32_e32 v17, v17
	v_cmp_lt_f32_e32 vcc, s76, v24
	v_add_f32_e32 v16, v199, v16
	s_nop 0
	v_cndmask_b32_e32 v174, 0, v17, vcc
	v_sub_f32_e32 v17, v25, v53
	v_exp_f32_e32 v17, v17
	v_cmp_lt_f32_e32 vcc, s76, v25
	v_add_f32_e32 v16, v174, v16
	s_nop 0
	v_cndmask_b32_e32 v176, 0, v17, vcc
	v_sub_f32_e32 v17, v26, v53
	v_exp_f32_e32 v17, v17
	v_cmp_lt_f32_e32 vcc, s76, v26
	v_add_f32_e32 v16, v176, v16
	s_nop 0
	v_cndmask_b32_e32 v178, 0, v17, vcc
	v_sub_f32_e32 v17, v27, v53
	v_exp_f32_e32 v17, v17
	v_cmp_lt_f32_e32 vcc, s76, v27
	v_add_f32_e32 v16, v178, v16
	s_nop 0
	v_cndmask_b32_e32 v180, 0, v17, vcc
	v_sub_f32_e32 v17, v28, v53
	v_exp_f32_e32 v17, v17
	v_cmp_lt_f32_e32 vcc, s76, v28
	v_add_f32_e32 v16, v180, v16
	s_nop 0
	v_cndmask_b32_e32 v183, 0, v17, vcc
	v_sub_f32_e32 v17, v29, v53
	v_exp_f32_e32 v17, v17
	v_cmp_lt_f32_e32 vcc, s76, v29
	v_add_f32_e32 v16, v183, v16
	s_nop 0
	v_cndmask_b32_e32 v185, 0, v17, vcc
	v_sub_f32_e32 v17, v30, v53
	v_exp_f32_e32 v17, v17
	v_cmp_lt_f32_e32 vcc, s76, v30
	v_add_f32_e32 v16, v185, v16
	s_nop 0
	v_cndmask_b32_e32 v187, 0, v17, vcc
	v_sub_f32_e32 v17, v31, v53
	v_exp_f32_e32 v17, v17
	v_cmp_lt_f32_e32 vcc, s76, v31
	v_add_f32_e32 v16, v187, v16
	s_nop 0
	v_cndmask_b32_e32 v189, 0, v17, vcc
	v_cmp_lt_f32_e32 vcc, s76, v0
	v_sub_f32_e32 v0, v0, v53
	v_exp_f32_e32 v0, v0
	v_add_f32_e32 v16, v189, v16
	v_cndmask_b32_e32 v170, 0, v0, vcc
	v_cmp_lt_f32_e32 vcc, s76, v1
	v_sub_f32_e32 v1, v1, v53
	v_exp_f32_e32 v1, v1
	v_add_f32_e32 v0, v170, v16
	v_cndmask_b32_e32 v171, 0, v1, vcc
	v_sub_f32_e32 v1, v2, v53
	v_exp_f32_e32 v1, v1
	v_cmp_lt_f32_e32 vcc, s76, v2
	v_add_f32_e32 v0, v171, v0
	s_nop 0
	v_cndmask_b32_e32 v172, 0, v1, vcc
	v_sub_f32_e32 v1, v3, v53
	v_exp_f32_e32 v1, v1
	v_cmp_lt_f32_e32 vcc, s76, v3
	v_add_f32_e32 v0, v172, v0
	s_nop 0
	v_cndmask_b32_e32 v173, 0, v1, vcc
	v_sub_f32_e32 v1, v4, v53
	v_exp_f32_e32 v1, v1
	v_cmp_lt_f32_e32 vcc, s76, v4
	v_add_f32_e32 v0, v173, v0
	s_nop 0
	v_cndmask_b32_e32 v175, 0, v1, vcc
	v_sub_f32_e32 v1, v5, v53
	v_exp_f32_e32 v1, v1
	v_cmp_lt_f32_e32 vcc, s76, v5
	v_add_f32_e32 v0, v175, v0
	s_nop 0
	v_cndmask_b32_e32 v177, 0, v1, vcc
	v_sub_f32_e32 v1, v6, v53
	v_exp_f32_e32 v1, v1
	v_cmp_lt_f32_e32 vcc, s76, v6
	v_add_f32_e32 v0, v177, v0
	s_nop 0
	v_cndmask_b32_e32 v179, 0, v1, vcc
	v_sub_f32_e32 v1, v7, v53
	v_exp_f32_e32 v1, v1
	v_cmp_lt_f32_e32 vcc, s76, v7
	v_add_f32_e32 v0, v179, v0
	s_nop 0
	v_cndmask_b32_e32 v181, 0, v1, vcc
	v_sub_f32_e32 v1, v8, v53
	v_exp_f32_e32 v1, v1
	v_cmp_lt_f32_e32 vcc, s76, v8
	v_add_f32_e32 v0, v181, v0
	s_nop 0
	v_cndmask_b32_e32 v182, 0, v1, vcc
	v_sub_f32_e32 v1, v9, v53
	v_exp_f32_e32 v1, v1
	v_cmp_lt_f32_e32 vcc, s76, v9
	v_add_f32_e32 v0, v182, v0
	s_nop 0
	v_cndmask_b32_e32 v184, 0, v1, vcc
	v_sub_f32_e32 v1, v10, v53
	v_exp_f32_e32 v1, v1
	v_cmp_lt_f32_e32 vcc, s76, v10
	v_add_f32_e32 v0, v184, v0
	s_nop 0
	v_cndmask_b32_e32 v186, 0, v1, vcc
	v_sub_f32_e32 v1, v11, v53
	v_exp_f32_e32 v1, v1
	v_cmp_lt_f32_e32 vcc, s76, v11
	v_add_f32_e32 v0, v186, v0
	s_nop 0
	v_cndmask_b32_e32 v188, 0, v1, vcc
	v_sub_f32_e32 v1, v12, v53
	v_exp_f32_e32 v1, v1
	v_cmp_lt_f32_e32 vcc, s76, v12
	v_add_f32_e32 v0, v188, v0
	s_nop 0
	v_cndmask_b32_e32 v190, 0, v1, vcc
	v_sub_f32_e32 v1, v13, v53
	v_exp_f32_e32 v1, v1
	v_cmp_lt_f32_e32 vcc, s76, v13
	v_add_f32_e32 v0, v190, v0
	s_nop 0
	v_cndmask_b32_e32 v191, 0, v1, vcc
	v_sub_f32_e32 v1, v14, v53
	v_exp_f32_e32 v1, v1
	v_cmp_lt_f32_e32 vcc, s76, v14
	v_exp_f32_e32 v14, v52
	v_cvt_pk_bf16_f32 v52, v54, v55
	v_cndmask_b32_e32 v192, 0, v1, vcc
	v_sub_f32_e32 v1, v15, v53
	v_cvt_pk_bf16_f32 v53, v194, v195
	v_cvt_pk_bf16_f32 v54, v196, v197
	ds_read_b128 v[194:197], v165 offset:9216
	v_pk_mul_f32 v[16:17], v[122:123], v[14:15] op_sel_hi:[1,0]
	v_pk_mul_f32 v[18:19], v[124:125], v[14:15] op_sel_hi:[1,0]
	v_pk_mul_f32 v[20:21], v[126:127], v[14:15] op_sel_hi:[1,0]
	v_pk_mul_f32 v[22:23], v[128:129], v[14:15] op_sel_hi:[1,0]
	v_pk_mul_f32 v[24:25], v[130:131], v[14:15] op_sel_hi:[1,0]
	v_pk_mul_f32 v[26:27], v[132:133], v[14:15] op_sel_hi:[1,0]
	v_pk_mul_f32 v[28:29], v[134:135], v[14:15] op_sel_hi:[1,0]
	v_pk_mul_f32 v[30:31], v[136:137], v[14:15] op_sel_hi:[1,0]
	v_cvt_pk_bf16_f32 v55, v198, v199
	v_exp_f32_e32 v1, v1
	v_add_f32_e32 v0, v191, v0
	s_waitcnt lgkmcnt(0)
; #define MFMA32(a, b, c) __builtin_amdgcn_mfma_f32_32x32x16_bf16((a), (b), (c), 0, 0, 0)
; template <int KSTRIDE, bool WIN, int MASK, int MODE>
; DI void attend_tile(const u16* Ks, const u16* Vts, const bf16x8 (&qf)[4], f32x16 (&O)[2], float& m, float& l, int dbase,
;                     float slope2, bool lanesel, float invl, unsigned* imp_row, int mbase, int lr, int hh) {
;   f32x16 s[2];
; #pragma unroll
;   for (int kt = 0; kt < 2; ++kt) {
; #pragma unroll
;     for (int e = 0; e < 16; ++e) s[kt][e] = 0.f;
; #pragma unroll
;     for (int ks = 0; ks < 4; ++ks) {
;       bf16x8 a = *(const bf16x8*)(Ks + (kt * 32 + lr) * 72 + ks * 16 + hh * 8);
;       s[kt] = MFMA32(a, qf[ks], s[kt]);
;     }
;   }
;   const float fd0 = (float)(dbase - KSTRIDE * 4 * hh);
;   const float ct = slope2 * fd0;
;   float mx = -1e30f;
; #pragma unroll
;   for (int kt = 0; kt < 2; ++kt)
; #pragma unroll
;     for (int e = 0; e < 16; ++e) {
;       const float Ke = (float)(KSTRIDE * (kt * 32 + (e & 3) + 8 * (e >> 2)));
;       float v = fmaf(slope2, Ke, s[kt][e]);
;       if (MASK == 1) {
;         const float fd = fd0 - Ke;
;         bool valid = fd >= 0.f;
;         if (WIN) valid = valid && (fd < 512.f);
;         valid = valid && lanesel;
;         v = valid ? v : -1e30f;
;       }
;       s[kt][e] = v;
;       mx = fmaxf(mx, v);
;     }
;   mx = (mx > -1e29f) ? mx - ct : -1e30f;
;   mx = fmaxf(mx, __shfl_xor(mx, 32));
;   if (MASK == 2) mx = lanesel ? mx : -1e30f;
;     ...
; #pragma unroll
;   for (int kt = 0; kt < 2; ++kt)
; #pragma unroll
;     for (int sx = 0; sx < 2; ++sx) {
;       unsigned pk[4];
; #pragma unroll
;       for (int q = 0; q < 4; ++q) pk[q] = pack2(s[kt][8 * sx + 2 * q], s[kt][8 * sx + 2 * q + 1]);
;       bf16x8 pb;
;       {
;         u32x4 t4 = {pk[0], pk[1], pk[2], pk[3]};
;         pb = __builtin_bit_cast(bf16x8, t4);
;       }
; #pragma unroll
;       for (int dt = 0; dt < 2; ++dt) {
;         bf16x8 a = *(const bf16x8*)(Vts + (dt * 32 + lr) * 72 + kt * 32 + 16 * sx + 8 * hh);
;         O[dt] = MFMA32(a, pb, O[dt]);
;       }
;     }
	v_mfma_f32_32x32x16_bf16 v[16:31], v[194:197], v[52:55], v[16:31]
	ds_read_b128 v[194:197], v165 offset:13824
	v_cmp_lt_f32_e32 vcc, s76, v15
	v_add_f32_e32 v0, v192, v0
	v_mul_f32_e64 v2, v140, v14
	v_mul_f32_e64 v3, v141, v14
	v_cndmask_b32_e32 v193, 0, v1, vcc
	v_add_f32_e32 v167, v193, v0
	v_fmac_f32_e32 v167, v168, v14
	v_pk_mul_f32 v[0:1], v[138:139], v[14:15] op_sel_hi:[1,0]
	v_pk_mul_f32 v[4:5], v[142:143], v[14:15] op_sel_hi:[1,0]
	v_pk_mul_f32 v[6:7], v[144:145], v[14:15] op_sel_hi:[1,0]
	v_pk_mul_f32 v[8:9], v[146:147], v[14:15] op_sel_hi:[1,0]
	v_pk_mul_f32 v[10:11], v[148:149], v[14:15] op_sel_hi:[1,0]
	v_pk_mul_f32 v[12:13], v[150:151], v[14:15] op_sel_hi:[1,0]
	v_pk_mul_f32 v[14:15], v[152:153], v[14:15] op_sel_hi:[1,0]
	s_mov_b64 vcc, 0
	s_waitcnt lgkmcnt(0)
	v_mfma_f32_32x32x16_bf16 v[0:15], v[194:197], v[52:55], v[0:15]
	ds_read_b128 v[194:197], v165 offset:9248
	v_cvt_pk_bf16_f32 v52, v174, v176
	v_cvt_pk_bf16_f32 v53, v178, v180
	v_cvt_pk_bf16_f32 v54, v183, v185
	v_cvt_pk_bf16_f32 v55, v187, v189
	s_waitcnt lgkmcnt(0)
	s_nop 0
	v_mfma_f32_32x32x16_bf16 v[16:31], v[194:197], v[52:55], v[16:31]
	ds_read_b128 v[194:197], v165 offset:13856
	s_waitcnt lgkmcnt(0)
	v_mfma_f32_32x32x16_bf16 v[0:15], v[194:197], v[52:55], v[0:15]
	v_cvt_pk_bf16_f32 v52, v170, v171
	v_cvt_pk_bf16_f32 v53, v172, v173
	ds_read_b128 v[170:173], v165 offset:9280
	v_cvt_pk_bf16_f32 v54, v175, v177
	v_cvt_pk_bf16_f32 v55, v179, v181
	s_waitcnt lgkmcnt(0)
	s_nop 0
	v_mfma_f32_32x32x16_bf16 v[16:31], v[170:173], v[52:55], v[16:31]
	ds_read_b128 v[170:173], v165 offset:13888
	s_waitcnt lgkmcnt(0)
	v_mfma_f32_32x32x16_bf16 v[0:15], v[170:173], v[52:55], v[0:15]
	ds_read_b128 v[170:173], v165 offset:9312
	v_cvt_pk_bf16_f32 v52, v182, v184
	v_cvt_pk_bf16_f32 v53, v186, v188
	v_cvt_pk_bf16_f32 v54, v190, v191
	v_cvt_pk_bf16_f32 v55, v192, v193
	s_waitcnt lgkmcnt(0)
	s_nop 0
	v_mfma_f32_32x32x16_bf16 v[16:31], v[170:173], v[52:55], v[16:31]
	ds_read_b128 v[170:173], v165 offset:13920
	s_waitcnt lgkmcnt(0)
	v_mfma_f32_32x32x16_bf16 v[0:15], v[170:173], v[52:55], v[0:15]
.LBB0_644:
	s_andn2_b64 vcc, exec, vcc
	s_cbranch_vccnz .LBB0_646
	s_waitcnt lgkmcnt(4)
	v_mfma_f32_32x32x16_bf16 v[16:31], v[48:51], v[64:67], 0
	s_lshl_b32 s80, s80, 6
	s_waitcnt lgkmcnt(3)
	v_mfma_f32_32x32x16_bf16 v[16:31], v[44:47], v[68:71], v[16:31]
	s_waitcnt lgkmcnt(2)
	v_mfma_f32_32x32x16_bf16 v[16:31], v[32:35], v[72:75], v[16:31]
	s_waitcnt lgkmcnt(0)
	v_mfma_f32_32x32x16_bf16 v[0:15], v[40:43], v[64:67], 0
	v_mfma_f32_32x32x16_bf16 v[16:31], v[36:39], v[76:79], v[16:31]
	ds_read_b128 v[32:35], v165 offset:4640
	ds_read_b128 v[36:39], v165 offset:4672
	s_waitcnt lgkmcnt(1)
	v_mfma_f32_32x32x16_bf16 v[0:15], v[32:35], v[68:71], v[0:15]
	ds_read_b128 v[32:35], v165 offset:4704
	s_nop 6
	v_fma_f32 v16, 0, v106, v16
	v_add_f32_e32 v17, v106, v17
	v_fma_f32 v18, 2.0, v106, v18
	v_fmamk_f32 v19, v106, 0x40400000, v19
	v_fmamk_f32 v20, v106, 0x41000000, v20
	v_fmamk_f32 v21, v106, 0x41100000, v21
	s_waitcnt lgkmcnt(1)
	v_mfma_f32_32x32x16_bf16 v[0:15], v[36:39], v[72:75], v[0:15]
	v_fmamk_f32 v22, v106, 0x41200000, v22
	v_fmamk_f32 v23, v106, 0x41300000, v23
	v_fmamk_f32 v24, v106, 0x41800000, v24
	v_fmamk_f32 v25, v106, 0x41880000, v25
	v_fmamk_f32 v26, v106, 0x41900000, v26
	v_fmamk_f32 v27, v106, 0x41980000, v27
	v_fmamk_f32 v28, v106, 0x41c00000, v28
	s_waitcnt lgkmcnt(0)
	v_mfma_f32_32x32x16_bf16 v[0:15], v[32:35], v[76:79], v[0:15]
	v_max3_f32 v33, v16, s95, v17
	v_max3_f32 v33, v33, v18, v19
	v_max3_f32 v33, v33, v20, v21
	v_max3_f32 v33, v33, v22, v23
	v_max3_f32 v33, v33, v24, v25
	v_max3_f32 v33, v33, v26, v27
	v_fmamk_f32 v29, v106, 0x41c80000, v29
	v_max3_f32 v33, v33, v28, v29
	v_fmamk_f32 v30, v106, 0x41d00000, v30
	v_fmac_f32_e32 v31, 0x41d80000, v106
	v_max3_f32 v33, v33, v30, v31
	s_nop 0
	v_fmamk_f32 v0, v106, 0x42000000, v0
	v_fmamk_f32 v1, v106, 0x42040000, v1
	v_max3_f32 v33, v33, v0, v1
	v_fmamk_f32 v2, v106, 0x42080000, v2
	v_fmamk_f32 v3, v106, 0x420c0000, v3
	v_max3_f32 v33, v33, v2, v3
	v_fmamk_f32 v4, v106, 0x42200000, v4
	v_fmamk_f32 v5, v106, 0x42240000, v5
	v_max3_f32 v33, v33, v4, v5
	v_fmamk_f32 v6, v106, 0x42280000, v6
	v_fmamk_f32 v7, v106, 0x422c0000, v7
	v_subrev_u32_e32 v32, s80, v57
	v_max3_f32 v33, v33, v6, v7
	v_fmamk_f32 v8, v106, 0x42400000, v8
	v_fmamk_f32 v9, v106, 0x42440000, v9
	v_cvt_f32_i32_e32 v32, v32
	v_max3_f32 v33, v33, v8, v9
	v_fmamk_f32 v10, v106, 0x42480000, v10
	v_fmamk_f32 v11, v106, 0x424c0000, v11
	v_max3_f32 v33, v33, v10, v11
	v_fmamk_f32 v12, v106, 0x42600000, v12
	v_fmamk_f32 v13, v106, 0x42640000, v13
	v_max3_f32 v33, v33, v12, v13
	v_fmamk_f32 v14, v106, 0x42680000, v14
	v_fmac_f32_e32 v15, 0x426c0000, v106
	v_max3_f32 v33, v33, v14, v15
	v_cmp_lt_f32_e32 vcc, s76, v33
	v_fma_f32 v33, -v106, v32, v33
	s_nop 0
	v_cndmask_b32_e32 v33, v160, v33, vcc
	v_mov_b32_e32 v34, v33
	s_nop 1
	v_permlane32_swap_b32_e32 v34, v33
	s_nop 1
	s_waitcnt lgkmcnt(0)
; #define MFMA32(a, b, c) __builtin_amdgcn_mfma_f32_32x32x16_bf16((a), (b), (c), 0, 0, 0)
; template <int KSTRIDE, bool WIN, int MASK, int MODE>
; DI void attend_tile(const u16* Ks, const u16* Vts, const bf16x8 (&qf)[4], f32x16 (&O)[2], float& m, float& l, int dbase,
;                     float slope2, bool lanesel, float invl, unsigned* imp_row, int mbase, int lr, int hh) {
;     ...
;   mx = (mx > -1e29f) ? mx - ct : -1e30f;
;   mx = fmaxf(mx, __shfl_xor(mx, 32));
;   if (MASK == 2) mx = lanesel ? mx : -1e30f;
;   float mnew = m, alpha = 1.f;
;   if (MODE != 2) {
;     mnew = fmaxf(m, mx);
;     alpha = fexp2(m - mnew);
;     m = mnew;
;   }
;   float shift = mnew + ct;
;   if (MASK == 2) shift = lanesel ? shift : 1e30f;
;   float rs = 0.f;
; #pragma unroll
;   for (int kt = 0; kt < 2; ++kt)
; #pragma unroll
;     for (int e = 0; e < 16; ++e) {
;       float v = s[kt][e];
;       float pv;
;       if (MASK == 1) pv = (v > -1e29f) ? fexp2(v - shift) : 0.f;
;       else pv = fexp2(v - shift);
;       if (MODE == 2) pv *= invl;
;       s[kt][e] = pv;
;       rs += pv;
;     }
;   if (MODE != 2) l = l * alpha + rs;
;   if (MODE == 1) return;
;   if (MODE == 0) {
; #pragma unroll
;     for (int e = 0; e < 16; ++e) { O[0][e] *= alpha; O[1][e] *= alpha; }
;   }
;   if (MODE == 2) {
; #pragma unroll
;     for (int kt = 0; kt < 2; ++kt)
; #pragma unroll
;       for (int q4 = 0; q4 < 4; ++q4) {
;         float qsum = s[kt][q4 * 4] + s[kt][q4 * 4 + 1] + s[kt][q4 * 4 + 2] + s[kt][q4 * 4 + 3];
;         float last = s[kt][q4 * 4 + 3];
;         int mi = mbase + kt * 8 + 2 * q4 + hh;
;         atomicAdd(imp_row + mi, (unsigned)(qsum * 1048576.f + 0.5f));
;         if (mi + 1 < 64) atomicAdd(imp_row + mi + 1, (unsigned)(last * 1048576.f + 0.5f));
;       }
;   }
; #pragma unroll
;   for (int kt = 0; kt < 2; ++kt)
; #pragma unroll
;     for (int sx = 0; sx < 2; ++sx) {
;       unsigned pk[4];
; #pragma unroll
;       for (int q = 0; q < 4; ++q) pk[q] = pack2(s[kt][8 * sx + 2 * q], s[kt][8 * sx + 2 * q + 1]);
;       bf16x8 pb;
;       {
;         u32x4 t4 = {pk[0], pk[1], pk[2], pk[3]};
;         pb = __builtin_bit_cast(bf16x8, t4);
;       }
; #pragma unroll
;       for (int dt = 0; dt < 2; ++dt) {
;         bf16x8 a = *(const bf16x8*)(Vts + (dt * 32 + lr) * 72 + kt * 32 + 16 * sx + 8 * hh);
;         O[dt] = MFMA32(a, pb, O[dt]);
;       }
;     }
	v_max_f32_e32 v34, v34, v34
	v_max_f32_e32 v33, v33, v34
	v_cndmask_b32_e64 v33, v160, v33, s[0:1]
	v_max_f32_e32 v34, v169, v169
	v_max_f32_e32 v166, v34, v33
	v_fma_f32 v32, v106, v32, v166
	v_cndmask_b32_e64 v32, v155, v32, s[0:1]
	v_sub_f32_e32 v16, v16, v32
	v_exp_f32_e32 v34, v16
	v_sub_f32_e32 v17, v17, v32
	v_exp_f32_e32 v35, v17
	v_sub_f32_e32 v17, v18, v32
	v_exp_f32_e32 v173, v17
	v_sub_f32_e32 v17, v19, v32
	v_exp_f32_e32 v174, v17
	v_sub_f32_e32 v17, v20, v32
	v_sub_f32_e32 v1, v1, v32
	v_add_f32_e32 v16, 0, v34
	v_exp_f32_e32 v175, v17
	v_sub_f32_e32 v17, v21, v32
	v_exp_f32_e32 v37, v1
	v_sub_f32_e32 v1, v2, v32
	v_add_f32_e32 v16, v35, v16
	v_exp_f32_e32 v176, v17
	v_sub_f32_e32 v17, v22, v32
	v_exp_f32_e32 v38, v1
	v_sub_f32_e32 v1, v3, v32
	v_add_f32_e32 v16, v173, v16
	v_exp_f32_e32 v177, v17
	v_sub_f32_e32 v17, v23, v32
	v_exp_f32_e32 v39, v1
	v_sub_f32_e32 v1, v4, v32
	v_add_f32_e32 v16, v174, v16
	v_exp_f32_e32 v178, v17
	v_sub_f32_e32 v17, v24, v32
	v_exp_f32_e32 v40, v1
	v_sub_f32_e32 v1, v5, v32
	v_add_f32_e32 v16, v175, v16
	v_exp_f32_e32 v51, v17
	v_sub_f32_e32 v17, v25, v32
	v_exp_f32_e32 v41, v1
	v_sub_f32_e32 v1, v6, v32
	v_add_f32_e32 v16, v176, v16
	v_exp_f32_e32 v53, v17
	v_sub_f32_e32 v17, v26, v32
	v_exp_f32_e32 v42, v1
	v_sub_f32_e32 v1, v7, v32
	v_add_f32_e32 v16, v177, v16
	v_exp_f32_e32 v54, v17
	v_sub_f32_e32 v17, v27, v32
	v_exp_f32_e32 v44, v1
	v_sub_f32_e32 v1, v8, v32
	v_add_f32_e32 v16, v178, v16
	v_exp_f32_e32 v55, v17
	v_sub_f32_e32 v17, v28, v32
	v_exp_f32_e32 v43, v1
	v_sub_f32_e32 v1, v9, v32
	v_sub_f32_e32 v33, v169, v166
	v_add_f32_e32 v16, v51, v16
	v_exp_f32_e32 v169, v17
	v_sub_f32_e32 v17, v29, v32
	v_exp_f32_e32 v45, v1
	v_sub_f32_e32 v1, v10, v32
	v_add_f32_e32 v16, v53, v16
	v_exp_f32_e32 v170, v17
	v_sub_f32_e32 v17, v30, v32
	v_exp_f32_e32 v46, v1
	v_sub_f32_e32 v1, v11, v32
	v_add_f32_e32 v16, v54, v16
	v_exp_f32_e32 v171, v17
	v_sub_f32_e32 v17, v31, v32
	v_exp_f32_e32 v47, v1
	v_sub_f32_e32 v1, v12, v32
	v_add_f32_e32 v16, v55, v16
	v_exp_f32_e32 v172, v17
	v_sub_f32_e32 v0, v0, v32
	v_exp_f32_e32 v48, v1
	v_sub_f32_e32 v1, v13, v32
	v_add_f32_e32 v16, v169, v16
	v_exp_f32_e32 v36, v0
	v_exp_f32_e32 v49, v1
	v_sub_f32_e32 v1, v14, v32
	v_exp_f32_e32 v14, v33
	v_add_f32_e32 v16, v170, v16
	v_add_f32_e32 v16, v171, v16
	v_add_f32_e32 v16, v172, v16
	v_add_f32_e32 v0, v36, v16
	v_pk_mul_f32 v[16:17], v[122:123], v[14:15] op_sel_hi:[1,0]
	v_pk_mul_f32 v[18:19], v[124:125], v[14:15] op_sel_hi:[1,0]
	ds_read_b128 v[122:125], v165 offset:9216
	v_add_f32_e32 v0, v37, v0
	v_add_f32_e32 v0, v38, v0
	v_add_f32_e32 v0, v39, v0
	v_add_f32_e32 v0, v40, v0
	v_add_f32_e32 v0, v41, v0
	v_add_f32_e32 v0, v42, v0
	v_add_f32_e32 v0, v44, v0
	v_exp_f32_e32 v50, v1
	v_sub_f32_e32 v1, v15, v32
	v_pk_mul_f32 v[20:21], v[126:127], v[14:15] op_sel_hi:[1,0]
	v_pk_mul_f32 v[22:23], v[128:129], v[14:15] op_sel_hi:[1,0]
	v_pk_mul_f32 v[24:25], v[130:131], v[14:15] op_sel_hi:[1,0]
	v_pk_mul_f32 v[26:27], v[132:133], v[14:15] op_sel_hi:[1,0]
	v_pk_mul_f32 v[28:29], v[134:135], v[14:15] op_sel_hi:[1,0]
	v_pk_mul_f32 v[30:31], v[136:137], v[14:15] op_sel_hi:[1,0]
	v_cvt_pk_bf16_f32 v32, v34, v35
	v_cvt_pk_bf16_f32 v33, v173, v174
	v_cvt_pk_bf16_f32 v34, v175, v176
	v_cvt_pk_bf16_f32 v35, v177, v178
	v_add_f32_e32 v0, v43, v0
	v_add_f32_e32 v0, v45, v0
	s_waitcnt lgkmcnt(0)
	v_mfma_f32_32x32x16_bf16 v[16:31], v[122:125], v[32:35], v[16:31]
	ds_read_b128 v[122:125], v165 offset:13824
	v_add_f32_e32 v0, v46, v0
	v_add_f32_e32 v0, v47, v0
	v_exp_f32_e32 v52, v1
	v_add_f32_e32 v0, v48, v0
	v_add_f32_e32 v0, v49, v0
	v_add_f32_e32 v0, v50, v0
	v_add_f32_e32 v167, v52, v0
	v_fmac_f32_e32 v167, v168, v14
	v_pk_mul_f32 v[0:1], v[138:139], v[14:15] op_sel_hi:[1,0]
	v_pk_mul_f32 v[2:3], v[140:141], v[14:15] op_sel_hi:[1,0]
	v_pk_mul_f32 v[4:5], v[142:143], v[14:15] op_sel_hi:[1,0]
	v_pk_mul_f32 v[6:7], v[144:145], v[14:15] op_sel_hi:[1,0]
	v_pk_mul_f32 v[8:9], v[146:147], v[14:15] op_sel_hi:[1,0]
	v_pk_mul_f32 v[10:11], v[148:149], v[14:15] op_sel_hi:[1,0]
	v_pk_mul_f32 v[12:13], v[150:151], v[14:15] op_sel_hi:[1,0]
	v_pk_mul_f32 v[14:15], v[152:153], v[14:15] op_sel_hi:[1,0]
	s_waitcnt lgkmcnt(0)
	s_nop 0
	v_mfma_f32_32x32x16_bf16 v[0:15], v[122:125], v[32:35], v[0:15]
	ds_read_b128 v[122:125], v165 offset:9248
	v_cvt_pk_bf16_f32 v32, v51, v53
	v_cvt_pk_bf16_f32 v33, v54, v55
	v_cvt_pk_bf16_f32 v34, v169, v170
	v_cvt_pk_bf16_f32 v35, v171, v172
	s_waitcnt lgkmcnt(0)
	s_nop 0
	v_mfma_f32_32x32x16_bf16 v[16:31], v[122:125], v[32:35], v[16:31]
	ds_read_b128 v[122:125], v165 offset:13856
	s_waitcnt lgkmcnt(0)
	v_mfma_f32_32x32x16_bf16 v[0:15], v[122:125], v[32:35], v[0:15]
	v_cvt_pk_bf16_f32 v32, v36, v37
	v_cvt_pk_bf16_f32 v33, v38, v39
	ds_read_b128 v[36:39], v165 offset:9280
	v_cvt_pk_bf16_f32 v34, v40, v41
	v_cvt_pk_bf16_f32 v35, v42, v44
	s_waitcnt lgkmcnt(0)
	s_nop 0
	v_mfma_f32_32x32x16_bf16 v[16:31], v[36:39], v[32:35], v[16:31]
	ds_read_b128 v[36:39], v165 offset:13888
	s_waitcnt lgkmcnt(0)
	v_mfma_f32_32x32x16_bf16 v[0:15], v[36:39], v[32:35], v[0:15]
	ds_read_b128 v[36:39], v165 offset:9312
	v_cvt_pk_bf16_f32 v32, v43, v45
	v_cvt_pk_bf16_f32 v33, v46, v47
	v_cvt_pk_bf16_f32 v34, v48, v49
	v_cvt_pk_bf16_f32 v35, v50, v52
	s_waitcnt lgkmcnt(0)
	s_nop 0
	v_mfma_f32_32x32x16_bf16 v[16:31], v[36:39], v[32:35], v[16:31]
	ds_read_b128 v[36:39], v165 offset:13920
	s_waitcnt lgkmcnt(0)
	v_mfma_f32_32x32x16_bf16 v[0:15], v[36:39], v[32:35], v[0:15]
